# kv GEMM epilogue (k head rmsnorm + rope): the eight k_pe row loads hoisted to the top of the epilogue into dead fragment registers; lane^16 exchanges via v_permlane16_swap + select instead of ds_bperm
# speedup vs baseline: 1.0805x; 1.0030x over previous
;     __device__ __forceinline__ void operator()(const f32x4 (&acc)[2][2][4][2], const Unit& u, int wr, int wc, int fr, int fq) const {
;     ...
;             for (int bj = 0; bj < 2; ++bj) { g0[bj] = *(const f32x4*)(gk + 32 * bj + 8 * fq); g1[bj] = *(const f32x4*)(gk + 32 * bj + 8 * fq + 4); }
;             const f32x4 gp0 = *(const f32x4*)(gk + 64 + 8 * fq), gp1 = *(const f32x4*)(gk + 64 + 8 * fq + 4);
;             const float invf[8] = {1.0f, 0.31622776601683794f, 0.1f, 0.031622776601683794f, 0.01f, 0.0031622776601683794f, 0.001f, 0.00031622776601683794f};
;             const float sgn = (fq & 1) ? 1.0f : -1.0f;
; #pragma unroll
;             for (int ai = 0; ai < 2; ++ai)
; #pragma unroll
;                 for (int m = 0; m < 4; ++m) { const int row = row0 + ai * HALF + m * 16, sp = sp0 + ai * HALF + m * 16;
;                     const u32x4 praw = *(const u32x4*)(KPE + (size_t)row * 32 + 8 * fq); float pe[8];
; #pragma unroll
;                     for (int e = 0; e < 4; ++e) { pe[2 * e] = __uint_as_float(praw[e] << 16); pe[2 * e + 1] = __uint_as_float(praw[e] & 0xffff0000u); }
;                     float ss = 0.f;
; #pragma unroll
;                     for (int bj = 0; bj < 2; ++bj)
; #pragma unroll
;                         for (int n = 0; n < 2; ++n) { const f32x4 v = acc[ai][bj][m][n]; ss += (v[0] * v[0] + v[1] * v[1]) + (v[2] * v[2] + v[3] * v[3]); }
; #pragma unroll
;                     for (int e = 0; e < 8; ++e) ss += pe[e] * pe[e];
;                     ss += __shfl_xor(ss, 16); ss += __shfl_xor(ss, 32);
;                     const float rstd = rsqrtf(ss * (1.0f / 96.0f) + EPS);
;                     bf16_t* kd = KH + ((size_t)(b * NHEAD + h) * SPB + sp) * 128;
; #pragma unroll
;                     for (int bj = 0; bj < 2; ++bj) *(u32x4*)(kd + 32 * bj + 8 * fq) = pack8(acc[ai][bj][m][0] * rstd * g0[bj], acc[ai][bj][m][1] * rstd * g1[bj]);
;                     const int l = sp - CTXL; const float pos = (fq >> 1) ? (float)(l & 63) : (float)(l >> 6);
;                     f32x4 o0, o1;
; #pragma unroll
;                     for (int e = 0; e < 8; ++e) { const float own = pe[e] * rstd * (e < 4 ? gp0[e & 3] : gp1[e & 3]); const float other = __shfl_xor(own, 16);
.LBB0_1508:
	s_mov_b32 s100, 0xffff0000
	s_mov_b32 s101, 0xffff0000
	v_add_u32_e32 v182, s35, v190
	v_ashrrev_i32_e32 v183, 31, v182
	v_lshlrev_b64 v[68:69], 6, v[182:183]
	v_lshl_add_u64 v[68:69], v[168:169], 0, v[68:69]
	global_load_dwordx4 v[204:207], v[68:69], off
	s_mov_b64 vcc, 0x2000
	global_load_dwordx4 v[220:223], v[68:69], off offset:1024
	global_load_dwordx4 v[224:227], v[68:69], off offset:2048
	global_load_dwordx4 v[228:231], v[68:69], off offset:3072
	v_lshl_add_u64 v[248:249], v[68:69], 0, vcc
	global_load_dwordx4 v[232:235], v[248:249], off
	global_load_dwordx4 v[236:239], v[248:249], off offset:1024
	global_load_dwordx4 v[240:243], v[248:249], off offset:2048
	global_load_dwordx4 v[244:247], v[248:249], off offset:3072
	global_load_dwordx4 v[80:83], v[170:171], off offset:16
	global_load_dwordx4 v[88:91], v[170:171], off
	global_load_dwordx4 v[76:79], v[170:171], off offset:144
	global_load_dwordx4 v[84:87], v[170:171], off offset:128
	s_nop 0
	global_load_dwordx4 v[68:71], v[170:171], off offset:272
	global_load_dwordx4 v[72:75], v[170:171], off offset:256
	v_and_b32_e32 v186, 64, v201
	v_xor_b32_e32 v164, 16, v201
	v_add_u32_e32 v186, 64, v186
	v_xor_b32_e32 v187, 32, v201
	v_mul_f32_e32 v202, v153, v153
	v_mul_f32_e32 v203, v155, v155
	v_mul_f32_e32 v208, v149, v149
	v_mul_f32_e32 v209, v151, v151
	v_cmp_lt_i32_e32 vcc, v164, v186
	v_mul_f32_e32 v210, v145, v145
	v_mul_f32_e32 v211, v147, v147
	v_fmac_f32_e32 v202, v152, v152
	v_fmac_f32_e32 v203, v154, v154
	v_fmac_f32_e32 v208, v148, v148
	v_fmac_f32_e32 v209, v150, v150
	v_cndmask_b32_e32 v164, v201, v164, vcc
	v_cmp_lt_i32_e32 vcc, v187, v186
	v_mul_f32_e32 v212, v141, v141
	v_mul_f32_e32 v213, v143, v143
	v_fmac_f32_e32 v210, v144, v144
	v_fmac_f32_e32 v211, v146, v146
	v_cndmask_b32_e32 v218, v201, v187, vcc
	v_add_f32_e32 v186, v202, v203
	v_add_f32_e32 v187, v208, v209
	v_fmac_f32_e32 v212, v140, v140
	v_fmac_f32_e32 v213, v142, v142
	v_add_f32_e32 v203, v210, v211
	v_lshlrev_b32_e32 v202, 2, v164
	v_add_f32_e32 v164, v187, v186
	v_add_f32_e32 v208, v212, v213
	v_add_f32_e32 v164, v203, v164
	v_add_f32_e32 v164, v208, v164
	v_lshlrev_b32_e32 v203, 2, v218
	s_lshl_b32 s4, s33, 2
	s_lshl_b32 s5, s34, 4
	s_or_b32 s4, s4, s53
	v_mov_b32_e32 v185, v165
	s_add_i32 s34, s4, s5
	s_mul_hi_i32 s5, s34, 0x1100
	s_mul_i32 s4, s34, 0x1100
	s_add_i32 s33, s27, 0xffffff00
	s_ashr_i32 s33, s33, 6
	s_waitcnt vmcnt(0)
	v_and_b32_e32 v208, 0xffff0000, v204
	v_lshlrev_b32_e32 v209, 16, v204
	v_pk_mul_f32 v[186:187], v[208:209], v[208:209]
	v_and_b32_e32 v210, 0xffff0000, v205
	v_lshlrev_b32_e32 v211, 16, v205
	v_add_f32_e32 v164, v164, v187
	v_pk_mul_f32 v[204:205], v[210:211], v[210:211]
	v_add_f32_e32 v164, v186, v164
	v_and_b32_e32 v212, 0xffff0000, v206
	v_lshlrev_b32_e32 v213, 16, v206
	v_add_f32_e32 v164, v205, v164
	v_pk_mul_f32 v[214:215], v[212:213], v[212:213]
	v_add_f32_e32 v164, v204, v164
	v_and_b32_e32 v206, 0xffff0000, v207
	v_lshlrev_b32_e32 v207, 16, v207
	v_add_f32_e32 v164, v215, v164
	v_pk_mul_f32 v[216:217], v[206:207], v[206:207]
	v_add_f32_e32 v164, v214, v164
	v_add_f32_e32 v164, v217, v164
	v_add_f32_e32 v164, v216, v164
	v_mov_b32_e32 v250, v164
	v_mov_b32_e32 v219, v164
	s_nop 1
	v_permlane16_swap_b32_e32 v250, v219
	v_cndmask_b32_e64 v186, v219, v250, s[100:101]
	v_cvt_f32_i32_e32 v204, s33
	s_waitcnt lgkmcnt(0)
	v_add_f32_e32 v164, v164, v186
	ds_bpermute_b32 v205, v203, v164
	v_mad_i64_i32 v[186:187], s[34:35], s34, v200, v[184:185]
	v_lshlrev_b64 v[186:187], 8, v[186:187]
	v_lshl_add_u64 v[186:187], v[172:173], 0, v[186:187]
	s_waitcnt lgkmcnt(0)
	v_add_f32_e32 v164, v164, v205
	v_fmamk_f32 v164, v164, 0x3c2aaaab, v199
	v_mul_f32_e32 v185, 0x4b800000, v164
	v_cmp_gt_f32_e32 vcc, s69, v164
	s_nop 1
	v_cndmask_b32_e32 v164, v164, v185, vcc
	v_rsq_f32_e32 v164, v164
	v_cndmask_b32_e64 v185, v192, v204, s[8:9]
	v_mul_f32_e32 v205, 0.15915494, v185
	v_cos_f32_e32 v218, v205
	v_mul_f32_e32 v214, 0x45800000, v164
	v_cndmask_b32_e32 v164, v164, v214, vcc
	v_pk_mul_f32 v[152:153], v[152:153], v[164:165] op_sel_hi:[1,0]
	v_pk_mul_f32 v[144:145], v[144:145], v[164:165] op_sel_hi:[1,0]
	v_pk_mul_f32 v[140:141], v[140:141], v[164:165] op_sel_hi:[1,0]
	v_pk_mul_f32 v[154:155], v[154:155], v[164:165] op_sel_hi:[1,0]
	v_pk_mul_f32 v[148:149], v[148:149], v[164:165] op_sel_hi:[1,0]
	v_pk_mul_f32 v[150:151], v[150:151], v[164:165] op_sel_hi:[1,0]
	v_pk_mul_f32 v[142:143], v[142:143], v[164:165] op_sel_hi:[1,0]
	v_mul_f32_e32 v209, v164, v209
	v_pk_mul_f32 v[152:153], v[88:89], v[152:153]
	v_pk_mul_f32 v[144:145], v[84:85], v[144:145]
	v_pk_mul_f32 v[216:217], v[76:77], v[140:141]
	v_cvt_pk_bf16_f32 v140, v152, v153
	v_pk_mul_f32 v[154:155], v[90:91], v[154:155]
	v_pk_mul_f32 v[150:151], v[82:83], v[150:151]
	v_pk_mul_f32 v[148:149], v[80:81], v[148:149]
	v_pk_mul_f32 v[214:215], v[78:79], v[142:143]
	v_mul_f32_e32 v209, v72, v209
	v_cvt_pk_bf16_f32 v141, v154, v155
	v_cvt_pk_bf16_f32 v142, v148, v149
	v_cvt_pk_bf16_f32 v143, v150, v151
	global_store_dwordx4 v[186:187], v[140:143], off
	v_pk_mul_f32 v[146:147], v[146:147], v[164:165] op_sel_hi:[1,0]
	s_nop 0
	v_cvt_pk_bf16_f32 v140, v144, v145
	v_sin_f32_e32 v144, v205
	v_mov_b32_e32 v250, v209
	v_mov_b32_e32 v219, v209
	s_nop 1
	v_permlane16_swap_b32_e32 v250, v219
	v_cndmask_b32_e64 v145, v219, v250, s[100:101]
	v_pk_mul_f32 v[146:147], v[86:87], v[146:147]
	s_nop 0
	v_cvt_pk_bf16_f32 v141, v146, v147
	v_cvt_pk_bf16_f32 v142, v216, v217
	v_cvt_pk_bf16_f32 v143, v214, v215
	global_store_dwordx4 v[186:187], v[140:143], off offset:64
	s_nop 1
	v_cndmask_b32_e64 v141, 0, v144, s[14:15]
	v_mul_f32_e32 v144, 0x3ea1e89b, v185
	v_mul_f32_e32 v143, v164, v208
	v_mul_f32_e32 v144, 0.15915494, v144
	s_waitcnt lgkmcnt(0)
; __device__ __forceinline__ u32x4 pack8(f32x4 v0, f32x4 v1) { u32x4 w; w.x = cvt_pk_bf16(v0[0], v0[1]); w.y = cvt_pk_bf16(v0[2], v0[3]); w.z = cvt_pk_bf16(v1[0], v1[1]); w.w = cvt_pk_bf16(v1[2], v1[3]); return w; }
;     __device__ __forceinline__ void operator()(const f32x4 (&acc)[2][2][4][2], const Unit& u, int wr, int wc, int fr, int fq) const {
;     ...
;                     const int l = sp - CTXL; const float pos = (fq >> 1) ? (float)(l & 63) : (float)(l >> 6);
;                     f32x4 o0, o1;
; #pragma unroll
;                     for (int e = 0; e < 8; ++e) { const float own = pe[e] * rstd * (e < 4 ? gp0[e & 3] : gp1[e & 3]); const float other = __shfl_xor(own, 16);
;                         float cs = 1.f, sn = 0.f; if (lat) { const float ang = pos * invf[e]; cs = __cosf(ang); sn = __sinf(ang); }
;                         const float r = own * cs + sgn * other * sn; if (e < 4) o0[e & 3] = r; else o1[e & 3] = r; }
;                     *(u32x4*)(kd + 64 + 8 * fq) = pack8(o0, o1);
;                     if (fq < 2) *(u32x4*)(kd + 96 + 8 * fq) = (u32x4){fq == 0 ? 0x3F80u : 0u, 0u, 0u, 0u};
	v_cndmask_b32_e64 v142, v145, -v145, s[6:7]
	v_mul_f32_e32 v143, v73, v143
	v_cos_f32_e32 v145, v144
	v_sin_f32_e32 v144, v144
	v_mov_b32_e32 v250, v143
	v_mov_b32_e32 v219, v143
	s_nop 1
	v_permlane16_swap_b32_e32 v250, v219
	v_cndmask_b32_e64 v146, v219, v250, s[100:101]
	v_cndmask_b32_e64 v140, 1.0, v218, s[14:15]
	v_mul_f32_e32 v140, v140, v209
	v_fmac_f32_e32 v140, v141, v142
	v_cndmask_b32_e64 v141, 1.0, v145, s[14:15]
	v_mul_f32_e32 v145, 0x3dcccccd, v185
	v_cndmask_b32_e64 v142, 0, v144, s[14:15]
	v_mul_f32_e32 v144, v164, v211
	v_mul_f32_e32 v145, 0.15915494, v145
	v_mul_f32_e32 v141, v141, v143
	s_waitcnt lgkmcnt(0)
	v_cndmask_b32_e64 v143, v146, -v146, s[6:7]
	v_mul_f32_e32 v144, v74, v144
	v_cos_f32_e32 v146, v145
	v_sin_f32_e32 v145, v145
	v_mov_b32_e32 v250, v144
	v_mov_b32_e32 v219, v144
	s_nop 1
	v_permlane16_swap_b32_e32 v250, v219
	v_cndmask_b32_e64 v147, v219, v250, s[100:101]
	v_fmac_f32_e32 v141, v142, v143
	v_cndmask_b32_e64 v142, 1.0, v146, s[14:15]
	v_mul_f32_e32 v146, 0x3d0186e2, v185
	v_cndmask_b32_e64 v143, 0, v145, s[14:15]
	v_mul_f32_e32 v145, v164, v210
	v_mul_f32_e32 v146, 0.15915494, v146
	v_mul_f32_e32 v142, v142, v144
	s_waitcnt lgkmcnt(0)
	v_cndmask_b32_e64 v144, v147, -v147, s[6:7]
	v_mul_f32_e32 v145, v75, v145
	v_cos_f32_e32 v147, v146
	v_sin_f32_e32 v146, v146
	v_mov_b32_e32 v250, v145
	v_mov_b32_e32 v219, v145
	s_nop 1
	v_permlane16_swap_b32_e32 v250, v219
	v_cndmask_b32_e64 v148, v219, v250, s[100:101]
	v_fmac_f32_e32 v142, v143, v144
	v_cndmask_b32_e64 v143, 1.0, v147, s[14:15]
	v_mul_f32_e32 v147, 0x3c23d70a, v185
	v_cndmask_b32_e64 v144, 0, v146, s[14:15]
	v_mul_f32_e32 v146, v164, v213
	v_mul_f32_e32 v147, 0.15915494, v147
	v_mul_f32_e32 v143, v143, v145
	s_waitcnt lgkmcnt(0)
	v_cndmask_b32_e64 v145, v148, -v148, s[6:7]
	v_mul_f32_e32 v146, v68, v146
	v_cos_f32_e32 v148, v147
	v_sin_f32_e32 v147, v147
	v_mov_b32_e32 v250, v146
	v_mov_b32_e32 v219, v146
	s_nop 1
	v_permlane16_swap_b32_e32 v250, v219
	v_cndmask_b32_e64 v149, v219, v250, s[100:101]
	v_fmac_f32_e32 v143, v144, v145
	v_cndmask_b32_e64 v144, 1.0, v148, s[14:15]
	v_mul_f32_e32 v148, 0x3b4f3e37, v185
	v_cndmask_b32_e64 v145, 0, v147, s[14:15]
	v_mul_f32_e32 v147, v164, v212
	v_mul_f32_e32 v148, 0.15915494, v148
	v_mul_f32_e32 v144, v144, v146
	s_waitcnt lgkmcnt(0)
	v_cndmask_b32_e64 v146, v149, -v149, s[6:7]
	v_mul_f32_e32 v147, v69, v147
	v_cos_f32_e32 v149, v148
	v_sin_f32_e32 v148, v148
	v_mov_b32_e32 v250, v147
	v_mov_b32_e32 v219, v147
	s_nop 1
	v_permlane16_swap_b32_e32 v250, v219
	v_cndmask_b32_e64 v150, v219, v250, s[100:101]
	v_fmac_f32_e32 v144, v145, v146
	v_cndmask_b32_e64 v145, 1.0, v149, s[14:15]
	v_mul_f32_e32 v149, 0x3a83126f, v185
	v_cndmask_b32_e64 v146, 0, v148, s[14:15]
	v_mul_f32_e32 v148, v164, v207
	v_mul_f32_e32 v149, 0.15915494, v149
	v_mul_f32_e32 v145, v145, v147
	s_waitcnt lgkmcnt(0)
	v_cndmask_b32_e64 v147, v150, -v150, s[6:7]
	v_mul_f32_e32 v148, v70, v148
	v_cos_f32_e32 v150, v149
	v_sin_f32_e32 v149, v149
	v_mov_b32_e32 v250, v148
	v_mov_b32_e32 v219, v148
	s_nop 1
	v_permlane16_swap_b32_e32 v250, v219
	v_cndmask_b32_e64 v151, v219, v250, s[100:101]
	v_fmac_f32_e32 v145, v146, v147
	v_cndmask_b32_e64 v146, 1.0, v150, s[14:15]
	v_cndmask_b32_e64 v147, 0, v149, s[14:15]
	v_mul_f32_e32 v149, v164, v206
	v_mul_f32_e32 v150, 0x39a5cb5f, v185
	v_mul_f32_e32 v149, v71, v149
	v_mul_f32_e32 v150, 0.15915494, v150
	v_mul_f32_e32 v146, v146, v148
	s_waitcnt lgkmcnt(0)
	v_cndmask_b32_e64 v148, v151, -v151, s[6:7]
	v_cos_f32_e32 v151, v150
	v_mov_b32_e32 v250, v149
	v_mov_b32_e32 v219, v149
	s_nop 1
	v_permlane16_swap_b32_e32 v250, v219
	v_cndmask_b32_e64 v152, v219, v250, s[100:101]
	v_sin_f32_e32 v150, v150
	v_fmac_f32_e32 v146, v147, v148
	v_cndmask_b32_e64 v147, 1.0, v151, s[14:15]
	v_mul_f32_e32 v147, v147, v149
	v_cndmask_b32_e64 v148, 0, v150, s[14:15]
	s_waitcnt lgkmcnt(0)
	v_cndmask_b32_e64 v149, v152, -v152, s[6:7]
	v_cvt_pk_bf16_f32 v140, v140, v141
	v_cvt_pk_bf16_f32 v141, v142, v143
	v_cvt_pk_bf16_f32 v142, v144, v145
	v_fmac_f32_e32 v147, v148, v149
	v_cvt_pk_bf16_f32 v143, v146, v147
	global_store_dwordx4 v[186:187], v[140:143], off offset:128
	s_nop 1
	v_mov_b32_e32 v142, v193
	s_and_saveexec_b64 s[34:35], s[8:9]
	s_cbranch_execz .LBB0_1510
	v_mov_b32_e32 v142, v204
	global_store_dwordx4 v[186:187], v[0:3], off offset:192
; __device__ __forceinline__ u32x4 pack8(f32x4 v0, f32x4 v1) { u32x4 w; w.x = cvt_pk_bf16(v0[0], v0[1]); w.y = cvt_pk_bf16(v0[2], v0[3]); w.z = cvt_pk_bf16(v1[0], v1[1]); w.w = cvt_pk_bf16(v1[2], v1[3]); return w; }
;     __device__ __forceinline__ void operator()(const f32x4 (&acc)[2][2][4][2], const Unit& u, int wr, int wc, int fr, int fq) const {
;     ...
;                 for (int m = 0; m < 4; ++m) { const int row = row0 + ai * HALF + m * 16, sp = sp0 + ai * HALF + m * 16;
;                     const u32x4 praw = *(const u32x4*)(KPE + (size_t)row * 32 + 8 * fq); float pe[8];
; #pragma unroll
;                     for (int e = 0; e < 4; ++e) { pe[2 * e] = __uint_as_float(praw[e] << 16); pe[2 * e + 1] = __uint_as_float(praw[e] & 0xffff0000u); }
;                     float ss = 0.f;
; #pragma unroll
;                     for (int bj = 0; bj < 2; ++bj)
; #pragma unroll
;                         for (int n = 0; n < 2; ++n) { const f32x4 v = acc[ai][bj][m][n]; ss += (v[0] * v[0] + v[1] * v[1]) + (v[2] * v[2] + v[3] * v[3]); }
; #pragma unroll
;                     for (int e = 0; e < 8; ++e) ss += pe[e] * pe[e];
;                     ss += __shfl_xor(ss, 16); ss += __shfl_xor(ss, 32);
;                     const float rstd = rsqrtf(ss * (1.0f / 96.0f) + EPS);
;                     bf16_t* kd = KH + ((size_t)(b * NHEAD + h) * SPB + sp) * 128;
; #pragma unroll
;                     for (int bj = 0; bj < 2; ++bj) *(u32x4*)(kd + 32 * bj + 8 * fq) = pack8(acc[ai][bj][m][0] * rstd * g0[bj], acc[ai][bj][m][1] * rstd * g1[bj]);
;                     const int l = sp - CTXL; const float pos = (fq >> 1) ? (float)(l & 63) : (float)(l >> 6);
;                     f32x4 o0, o1;
; #pragma unroll
;                     for (int e = 0; e < 8; ++e) { const float own = pe[e] * rstd * (e < 4 ? gp0[e & 3] : gp1[e & 3]); const float other = __shfl_xor(own, 16);
.LBB0_1510:
	s_or_b64 exec, exec, s[34:35]
	v_or_b32_e32 v140, 16, v182
	v_ashrrev_i32_e32 v141, 31, v140
	v_lshlrev_b64 v[140:141], 6, v[140:141]
	v_lshl_add_u64 v[140:141], v[168:169], 0, v[140:141]
	v_mov_b32_e32 v144, v220
	v_mov_b32_e32 v145, v221
	v_mov_b32_e32 v146, v222
	v_mov_b32_e32 v147, v223
	v_mul_f32_e32 v143, v137, v137
	v_mul_f32_e32 v148, v139, v139
	v_mul_f32_e32 v149, v133, v133
	v_mul_f32_e32 v150, v135, v135
	v_mul_f32_e32 v151, v129, v129
	v_mul_f32_e32 v152, v131, v131
	v_fmac_f32_e32 v143, v136, v136
	v_fmac_f32_e32 v148, v138, v138
	v_fmac_f32_e32 v149, v132, v132
	v_fmac_f32_e32 v150, v134, v134
	v_mul_f32_e32 v153, v125, v125
	v_mul_f32_e32 v154, v127, v127
	v_fmac_f32_e32 v151, v128, v128
	v_fmac_f32_e32 v152, v130, v130
	v_add_f32_e32 v143, v143, v148
	v_add_f32_e32 v148, v149, v150
	v_fmac_f32_e32 v153, v124, v124
	v_fmac_f32_e32 v154, v126, v126
	v_add_f32_e32 v149, v151, v152
	v_add_f32_e32 v143, v148, v143
	v_add_f32_e32 v150, v153, v154
	v_add_f32_e32 v143, v149, v143
	v_add_f32_e32 v143, v150, v143
	v_or_b32_e32 v164, 16, v184
	v_mul_f32_e32 v155, 0.15915494, v142
	v_lshl_add_u64 v[140:141], s[4:5], 0, v[164:165]
	v_cos_f32_e32 v164, v155
	v_sin_f32_e32 v205, v155
	v_mul_f32_e32 v186, 0x3dcccccd, v142
	v_mul_f32_e32 v208, 0.15915494, v186
	v_mul_f32_e32 v185, 0x3ea1e89b, v142
	v_mul_f32_e32 v185, 0.15915494, v185
	v_lshlrev_b64 v[140:141], 8, v[140:141]
	v_lshl_add_u64 v[140:141], v[172:173], 0, v[140:141]
	v_cndmask_b32_e64 v164, 1.0, v164, s[14:15]
	s_waitcnt vmcnt(0)
	v_and_b32_e32 v148, 0xffff0000, v144
	v_lshlrev_b32_e32 v149, 16, v144
	v_pk_mul_f32 v[152:153], v[148:149], v[148:149]
	v_and_b32_e32 v144, 0xffff0000, v145
	v_lshlrev_b32_e32 v145, 16, v145
	v_add_f32_e32 v143, v143, v153
	v_pk_mul_f32 v[154:155], v[144:145], v[144:145]
	v_add_f32_e32 v143, v152, v143
	v_and_b32_e32 v150, 0xffff0000, v146
	v_lshlrev_b32_e32 v151, 16, v146
	v_add_f32_e32 v143, v155, v143
	v_pk_mul_f32 v[186:187], v[150:151], v[150:151]
	v_add_f32_e32 v143, v154, v143
	v_and_b32_e32 v146, 0xffff0000, v147
	v_lshlrev_b32_e32 v147, 16, v147
	v_add_f32_e32 v143, v187, v143
	v_pk_mul_f32 v[206:207], v[146:147], v[146:147]
	v_add_f32_e32 v143, v186, v143
	v_add_f32_e32 v143, v207, v143
	v_add_f32_e32 v143, v206, v143
	v_mov_b32_e32 v250, v143
	v_mov_b32_e32 v219, v143
	s_nop 1
	v_permlane16_swap_b32_e32 v250, v219
	v_cndmask_b32_e64 v152, v219, v250, s[100:101]
	v_cos_f32_e32 v153, v185
	v_cndmask_b32_e64 v186, 0, v205, s[14:15]
	v_sin_f32_e32 v154, v185
	v_cos_f32_e32 v155, v208
	s_waitcnt lgkmcnt(0)
	v_add_f32_e32 v143, v143, v152
	ds_bpermute_b32 v152, v203, v143
	v_cndmask_b32_e64 v153, 1.0, v153, s[14:15]
	v_cndmask_b32_e64 v154, 0, v154, s[14:15]
	v_sin_f32_e32 v185, v208
	v_cndmask_b32_e64 v155, 1.0, v155, s[14:15]
	s_waitcnt lgkmcnt(0)
	v_add_f32_e32 v143, v143, v152
	v_fmamk_f32 v143, v143, 0x3c2aaaab, v199
	v_mul_f32_e32 v152, 0x4b800000, v143
	v_cmp_gt_f32_e32 vcc, s69, v143
	v_cndmask_b32_e64 v185, 0, v185, s[14:15]
	s_nop 0
	v_cndmask_b32_e32 v143, v143, v152, vcc
	v_rsq_f32_e32 v143, v143
	s_nop 0
	v_mul_f32_e32 v152, 0x45800000, v143
	v_cndmask_b32_e32 v152, v143, v152, vcc
	v_pk_mul_f32 v[134:135], v[134:135], v[152:153] op_sel_hi:[1,0]
	v_mul_f32_e32 v187, v152, v148
	v_pk_mul_f32 v[136:137], v[136:137], v[152:153] op_sel_hi:[1,0]
	v_pk_mul_f32 v[138:139], v[138:139], v[152:153] op_sel_hi:[1,0]
	v_pk_mul_f32 v[132:133], v[132:133], v[152:153] op_sel_hi:[1,0]
	v_pk_mul_f32 v[124:125], v[124:125], v[152:153] op_sel_hi:[1,0]
	v_pk_mul_f32 v[126:127], v[126:127], v[152:153] op_sel_hi:[1,0]
	v_mul_f32_e32 v143, v152, v149
	v_pk_mul_f32 v[134:135], v[82:83], v[134:135]
	v_mul_f32_e32 v187, v73, v187
	v_mul_f32_e32 v205, v152, v145
	v_mul_f32_e32 v206, v152, v144
	v_pk_mul_f32 v[138:139], v[90:91], v[138:139]
	v_pk_mul_f32 v[136:137], v[88:89], v[136:137]
	v_pk_mul_f32 v[132:133], v[80:81], v[132:133]
	v_pk_mul_f32 v[144:145], v[78:79], v[126:127]
	v_pk_mul_f32 v[148:149], v[76:77], v[124:125]
	v_mul_f32_e32 v143, v72, v143
	v_cvt_pk_bf16_f32 v124, v136, v137
	v_cvt_pk_bf16_f32 v125, v138, v139
	v_cvt_pk_bf16_f32 v126, v132, v133
	v_cvt_pk_bf16_f32 v127, v134, v135
	v_mov_b32_e32 v250, v187
	v_mov_b32_e32 v219, v187
	s_nop 1
	v_permlane16_swap_b32_e32 v250, v219
	v_cndmask_b32_e64 v134, v219, v250, s[100:101]
	v_mov_b32_e32 v250, v143
	v_mov_b32_e32 v219, v143
	s_nop 1
	v_permlane16_swap_b32_e32 v250, v219
	v_cndmask_b32_e64 v132, v219, v250, s[100:101]
	v_pk_mul_f32 v[128:129], v[128:129], v[152:153] op_sel_hi:[1,0]
	v_pk_mul_f32 v[130:131], v[130:131], v[152:153] op_sel_hi:[1,0]
	v_pk_mul_f32 v[128:129], v[84:85], v[128:129]
	v_pk_mul_f32 v[130:131], v[86:87], v[130:131]
	global_store_dwordx4 v[140:141], v[124:127], off
	v_mul_f32_e32 v205, v74, v205
	v_mul_f32_e32 v135, v153, v187
	v_cvt_pk_bf16_f32 v124, v128, v129
	v_cvt_pk_bf16_f32 v125, v130, v131
	v_cvt_pk_bf16_f32 v126, v148, v149
	v_cvt_pk_bf16_f32 v127, v144, v145
	global_store_dwordx4 v[140:141], v[124:127], off offset:64
	v_mul_f32_e32 v133, v164, v143
	v_mov_b32_e32 v250, v205
	v_mov_b32_e32 v219, v205
	s_nop 1
	v_permlane16_swap_b32_e32 v250, v219
	v_cndmask_b32_e64 v136, v219, v250, s[100:101]
	s_waitcnt lgkmcnt(2)
	v_cndmask_b32_e64 v125, v134, -v134, s[6:7]
	s_waitcnt lgkmcnt(1)
	v_cndmask_b32_e64 v124, v132, -v132, s[6:7]
	v_fmac_f32_e32 v135, v154, v125
	v_mul_f32_e32 v125, 0x3d0186e2, v142
	v_fmac_f32_e32 v133, v186, v124
	v_mul_f32_e32 v124, v75, v206
	v_mul_f32_e32 v125, 0.15915494, v125
	v_cos_f32_e32 v127, v125
	v_mov_b32_e32 v250, v124
	v_mov_b32_e32 v219, v124
	s_nop 1
	v_permlane16_swap_b32_e32 v250, v219
	v_cndmask_b32_e64 v128, v219, v250, s[100:101]
	v_mul_f32_e32 v137, v155, v205
	s_waitcnt lgkmcnt(1)
; __device__ __forceinline__ u32x4 pack8(f32x4 v0, f32x4 v1) { u32x4 w; w.x = cvt_pk_bf16(v0[0], v0[1]); w.y = cvt_pk_bf16(v0[2], v0[3]); w.z = cvt_pk_bf16(v1[0], v1[1]); w.w = cvt_pk_bf16(v1[2], v1[3]); return w; }
;     __device__ __forceinline__ void operator()(const f32x4 (&acc)[2][2][4][2], const Unit& u, int wr, int wc, int fr, int fq) const {
;     ...
;                 for (int m = 0; m < 4; ++m) { const int row = row0 + ai * HALF + m * 16, sp = sp0 + ai * HALF + m * 16;
;                     const u32x4 praw = *(const u32x4*)(KPE + (size_t)row * 32 + 8 * fq); float pe[8];
; #pragma unroll
;                     for (int e = 0; e < 4; ++e) { pe[2 * e] = __uint_as_float(praw[e] << 16); pe[2 * e + 1] = __uint_as_float(praw[e] & 0xffff0000u); }
;                     float ss = 0.f;
; #pragma unroll
;                     for (int bj = 0; bj < 2; ++bj)
; #pragma unroll
;                         for (int n = 0; n < 2; ++n) { const f32x4 v = acc[ai][bj][m][n]; ss += (v[0] * v[0] + v[1] * v[1]) + (v[2] * v[2] + v[3] * v[3]); }
; #pragma unroll
;                     for (int e = 0; e < 8; ++e) ss += pe[e] * pe[e];
;                     ss += __shfl_xor(ss, 16); ss += __shfl_xor(ss, 32);
;                     const float rstd = rsqrtf(ss * (1.0f / 96.0f) + EPS);
;                     bf16_t* kd = KH + ((size_t)(b * NHEAD + h) * SPB + sp) * 128;
; #pragma unroll
;                     for (int bj = 0; bj < 2; ++bj) *(u32x4*)(kd + 32 * bj + 8 * fq) = pack8(acc[ai][bj][m][0] * rstd * g0[bj], acc[ai][bj][m][1] * rstd * g1[bj]);
;                     const int l = sp - CTXL; const float pos = (fq >> 1) ? (float)(l & 63) : (float)(l >> 6);
;                     f32x4 o0, o1;
; #pragma unroll
;                     for (int e = 0; e < 8; ++e) { const float own = pe[e] * rstd * (e < 4 ? gp0[e & 3] : gp1[e & 3]); const float other = __shfl_xor(own, 16);
;                         float cs = 1.f, sn = 0.f; if (lat) { const float ang = pos * invf[e]; cs = __cosf(ang); sn = __sinf(ang); }
;                         const float r = own * cs + sgn * other * sn; if (e < 4) o0[e & 3] = r; else o1[e & 3] = r; }
;                     *(u32x4*)(kd + 64 + 8 * fq) = pack8(o0, o1);
;                     if (fq < 2) *(u32x4*)(kd + 96 + 8 * fq) = (u32x4){fq == 0 ? 0x3F80u : 0u, 0u, 0u, 0u};
	v_cndmask_b32_e64 v126, v136, -v136, s[6:7]
	v_fmac_f32_e32 v137, v185, v126
	v_cndmask_b32_e64 v126, 1.0, v127, s[14:15]
	v_mul_f32_e32 v126, v126, v124
	s_waitcnt lgkmcnt(0)
	v_cndmask_b32_e64 v124, v128, -v128, s[6:7]
	v_mul_f32_e32 v128, 0x3c23d70a, v142
	v_sin_f32_e32 v125, v125
	v_mul_f32_e32 v127, v152, v151
	v_mul_f32_e32 v128, 0.15915494, v128
	v_mul_f32_e32 v127, v68, v127
	v_cos_f32_e32 v129, v128
	v_sin_f32_e32 v128, v128
	v_mov_b32_e32 v250, v127
	v_mov_b32_e32 v219, v127
	s_nop 1
	v_permlane16_swap_b32_e32 v250, v219
	v_cndmask_b32_e64 v130, v219, v250, s[100:101]
	v_cndmask_b32_e64 v125, 0, v125, s[14:15]
	v_fmac_f32_e32 v126, v125, v124
	v_cndmask_b32_e64 v124, 1.0, v129, s[14:15]
	v_mul_f32_e32 v129, 0x3b4f3e37, v142
	v_cndmask_b32_e64 v125, 0, v128, s[14:15]
	v_mul_f32_e32 v128, v152, v150
	v_mul_f32_e32 v129, 0.15915494, v129
	v_mul_f32_e32 v127, v124, v127
	s_waitcnt lgkmcnt(0)
	v_cndmask_b32_e64 v124, v130, -v130, s[6:7]
	v_mul_f32_e32 v128, v69, v128
	v_cos_f32_e32 v130, v129
	v_sin_f32_e32 v129, v129
	v_mov_b32_e32 v250, v128
	v_mov_b32_e32 v219, v128
	s_nop 1
	v_permlane16_swap_b32_e32 v250, v219
	v_cndmask_b32_e64 v131, v219, v250, s[100:101]
	v_fmac_f32_e32 v127, v125, v124
	v_cndmask_b32_e64 v124, 1.0, v130, s[14:15]
	v_mul_f32_e32 v130, 0x3a83126f, v142
	v_cndmask_b32_e64 v125, 0, v129, s[14:15]
	v_mul_f32_e32 v129, v152, v147
	v_mul_f32_e32 v130, 0.15915494, v130
	v_mul_f32_e32 v128, v124, v128
	s_waitcnt lgkmcnt(0)
	v_cndmask_b32_e64 v124, v131, -v131, s[6:7]
	v_mul_f32_e32 v129, v70, v129
	v_cos_f32_e32 v131, v130
	v_sin_f32_e32 v130, v130
	v_mov_b32_e32 v250, v129
	v_mov_b32_e32 v219, v129
	s_nop 1
	v_permlane16_swap_b32_e32 v250, v219
	v_cndmask_b32_e64 v132, v219, v250, s[100:101]
	v_fmac_f32_e32 v128, v125, v124
	v_cndmask_b32_e64 v124, 1.0, v131, s[14:15]
	v_cndmask_b32_e64 v125, 0, v130, s[14:15]
	v_mul_f32_e32 v130, v152, v146
	v_mul_f32_e32 v131, 0x39a5cb5f, v142
	v_mul_f32_e32 v130, v71, v130
	v_mul_f32_e32 v131, 0.15915494, v131
	v_mul_f32_e32 v129, v124, v129
	s_waitcnt lgkmcnt(0)
	v_cndmask_b32_e64 v124, v132, -v132, s[6:7]
	v_cos_f32_e32 v132, v131
	v_mov_b32_e32 v250, v130
	v_mov_b32_e32 v219, v130
	s_nop 1
	v_permlane16_swap_b32_e32 v250, v219
	v_cndmask_b32_e64 v134, v219, v250, s[100:101]
	v_sin_f32_e32 v131, v131
	v_fmac_f32_e32 v129, v125, v124
	v_cndmask_b32_e64 v124, 1.0, v132, s[14:15]
	v_mul_f32_e32 v130, v124, v130
	v_cndmask_b32_e64 v125, 0, v131, s[14:15]
	s_waitcnt lgkmcnt(0)
	v_cndmask_b32_e64 v124, v134, -v134, s[6:7]
	v_fmac_f32_e32 v130, v125, v124
	v_cvt_pk_bf16_f32 v124, v133, v135
	v_cvt_pk_bf16_f32 v125, v137, v126
	v_cvt_pk_bf16_f32 v126, v127, v128
	v_cvt_pk_bf16_f32 v127, v129, v130
	global_store_dwordx4 v[140:141], v[124:127], off offset:128
	s_nop 1
	v_mov_b32_e32 v126, v194
	s_and_saveexec_b64 s[34:35], s[8:9]
	s_cbranch_execz .LBB0_1512
	v_mov_b32_e32 v126, v204
	global_store_dwordx4 v[140:141], v[0:3], off offset:192
.LBB0_1512:
	s_or_b64 exec, exec, s[34:35]
	v_or_b32_e32 v124, 32, v182
	v_ashrrev_i32_e32 v125, 31, v124
	v_lshlrev_b64 v[124:125], 6, v[124:125]
	v_lshl_add_u64 v[124:125], v[168:169], 0, v[124:125]
	v_mov_b32_e32 v128, v224
	v_mov_b32_e32 v129, v225
	v_mov_b32_e32 v130, v226
	v_mov_b32_e32 v131, v227
	v_mul_f32_e32 v127, v121, v121
	v_mul_f32_e32 v132, v123, v123
	v_mul_f32_e32 v133, v117, v117
	v_mul_f32_e32 v134, v119, v119
	v_mul_f32_e32 v135, v113, v113
	v_mul_f32_e32 v136, v115, v115
	v_fmac_f32_e32 v127, v120, v120
	v_fmac_f32_e32 v132, v122, v122
	v_fmac_f32_e32 v133, v116, v116
	v_fmac_f32_e32 v134, v118, v118
	v_mul_f32_e32 v137, v109, v109
	v_mul_f32_e32 v138, v111, v111
	v_fmac_f32_e32 v135, v112, v112
	v_fmac_f32_e32 v136, v114, v114
	v_add_f32_e32 v127, v127, v132
	v_add_f32_e32 v132, v133, v134
	v_fmac_f32_e32 v137, v108, v108
	v_fmac_f32_e32 v138, v110, v110
	v_add_f32_e32 v133, v135, v136
	v_add_f32_e32 v127, v132, v127
	v_add_f32_e32 v134, v137, v138
	v_add_f32_e32 v127, v133, v127
	v_add_f32_e32 v127, v134, v127
	v_mul_f32_e32 v139, 0.15915494, v126
	v_cos_f32_e32 v144, v139
	v_sin_f32_e32 v145, v139
	v_mul_f32_e32 v140, 0x3ea1e89b, v126
	v_mul_f32_e32 v141, 0x3dcccccd, v126
	v_mul_f32_e32 v146, 0.15915494, v140
	v_mul_f32_e32 v147, 0.15915494, v141
	v_or_b32_e32 v164, 32, v184
	v_lshl_add_u64 v[124:125], s[4:5], 0, v[164:165]
	v_lshlrev_b64 v[124:125], 8, v[124:125]
	v_lshl_add_u64 v[124:125], v[172:173], 0, v[124:125]
	s_waitcnt vmcnt(0)
	v_and_b32_e32 v132, 0xffff0000, v128
	v_lshlrev_b32_e32 v133, 16, v128
	v_pk_mul_f32 v[136:137], v[132:133], v[132:133]
	v_and_b32_e32 v128, 0xffff0000, v129
	v_lshlrev_b32_e32 v129, 16, v129
	v_add_f32_e32 v127, v127, v137
	v_pk_mul_f32 v[138:139], v[128:129], v[128:129]
	v_add_f32_e32 v127, v136, v127
	v_and_b32_e32 v134, 0xffff0000, v130
	v_lshlrev_b32_e32 v135, 16, v130
	v_add_f32_e32 v127, v139, v127
	v_pk_mul_f32 v[140:141], v[134:135], v[134:135]
	v_add_f32_e32 v127, v138, v127
	v_and_b32_e32 v130, 0xffff0000, v131
	v_lshlrev_b32_e32 v131, 16, v131
	v_add_f32_e32 v127, v141, v127
	v_pk_mul_f32 v[142:143], v[130:131], v[130:131]
	v_add_f32_e32 v127, v140, v127
	v_add_f32_e32 v127, v143, v127
	v_add_f32_e32 v127, v142, v127
	v_mov_b32_e32 v250, v127
	v_mov_b32_e32 v219, v127
	s_nop 1
	v_permlane16_swap_b32_e32 v250, v219
	v_cndmask_b32_e64 v136, v219, v250, s[100:101]
	v_cos_f32_e32 v137, v146
	v_cndmask_b32_e64 v141, 1.0, v144, s[14:15]
	v_cndmask_b32_e64 v142, 0, v145, s[14:15]
	v_sin_f32_e32 v138, v146
	s_waitcnt lgkmcnt(0)
	v_add_f32_e32 v127, v127, v136
	ds_bpermute_b32 v136, v203, v127
	v_cndmask_b32_e64 v137, 1.0, v137, s[14:15]
	v_cndmask_b32_e64 v138, 0, v138, s[14:15]
	v_cos_f32_e32 v139, v147
	v_sin_f32_e32 v140, v147
	s_waitcnt lgkmcnt(0)
; __device__ __forceinline__ u32x4 pack8(f32x4 v0, f32x4 v1) { u32x4 w; w.x = cvt_pk_bf16(v0[0], v0[1]); w.y = cvt_pk_bf16(v0[2], v0[3]); w.z = cvt_pk_bf16(v1[0], v1[1]); w.w = cvt_pk_bf16(v1[2], v1[3]); return w; }
;     __device__ __forceinline__ void operator()(const f32x4 (&acc)[2][2][4][2], const Unit& u, int wr, int wc, int fr, int fq) const {
;     ...
;                     ss += __shfl_xor(ss, 16); ss += __shfl_xor(ss, 32);
;                     const float rstd = rsqrtf(ss * (1.0f / 96.0f) + EPS);
;                     bf16_t* kd = KH + ((size_t)(b * NHEAD + h) * SPB + sp) * 128;
; #pragma unroll
;                     for (int bj = 0; bj < 2; ++bj) *(u32x4*)(kd + 32 * bj + 8 * fq) = pack8(acc[ai][bj][m][0] * rstd * g0[bj], acc[ai][bj][m][1] * rstd * g1[bj]);
;                     const int l = sp - CTXL; const float pos = (fq >> 1) ? (float)(l & 63) : (float)(l >> 6);
;                     f32x4 o0, o1;
; #pragma unroll
;                     for (int e = 0; e < 8; ++e) { const float own = pe[e] * rstd * (e < 4 ? gp0[e & 3] : gp1[e & 3]); const float other = __shfl_xor(own, 16);
;                         float cs = 1.f, sn = 0.f; if (lat) { const float ang = pos * invf[e]; cs = __cosf(ang); sn = __sinf(ang); }
;                         const float r = own * cs + sgn * other * sn; if (e < 4) o0[e & 3] = r; else o1[e & 3] = r; }
;                     *(u32x4*)(kd + 64 + 8 * fq) = pack8(o0, o1);
;                     if (fq < 2) *(u32x4*)(kd + 96 + 8 * fq) = (u32x4){fq == 0 ? 0x3F80u : 0u, 0u, 0u, 0u};
	v_add_f32_e32 v127, v127, v136
	v_fmamk_f32 v127, v127, 0x3c2aaaab, v199
	v_mul_f32_e32 v136, 0x4b800000, v127
	v_cmp_gt_f32_e32 vcc, s69, v127
	v_cndmask_b32_e64 v139, 1.0, v139, s[14:15]
	v_cndmask_b32_e64 v140, 0, v140, s[14:15]
	v_cndmask_b32_e32 v127, v127, v136, vcc
	v_rsq_f32_e32 v127, v127
	s_nop 0
	v_mul_f32_e32 v136, 0x45800000, v127
	v_cndmask_b32_e32 v136, v127, v136, vcc
	v_pk_mul_f32 v[118:119], v[118:119], v[136:137] op_sel_hi:[1,0]
	v_mul_f32_e32 v143, v136, v132
	v_pk_mul_f32 v[120:121], v[120:121], v[136:137] op_sel_hi:[1,0]
	v_pk_mul_f32 v[122:123], v[122:123], v[136:137] op_sel_hi:[1,0]
	v_pk_mul_f32 v[116:117], v[116:117], v[136:137] op_sel_hi:[1,0]
	v_pk_mul_f32 v[108:109], v[108:109], v[136:137] op_sel_hi:[1,0]
	v_pk_mul_f32 v[110:111], v[110:111], v[136:137] op_sel_hi:[1,0]
	v_mul_f32_e32 v127, v136, v133
	v_pk_mul_f32 v[118:119], v[82:83], v[118:119]
	v_mul_f32_e32 v143, v73, v143
	v_mul_f32_e32 v144, v136, v129
	v_mul_f32_e32 v145, v136, v128
	v_pk_mul_f32 v[122:123], v[90:91], v[122:123]
	v_pk_mul_f32 v[120:121], v[88:89], v[120:121]
	v_pk_mul_f32 v[116:117], v[80:81], v[116:117]
	v_pk_mul_f32 v[128:129], v[78:79], v[110:111]
	v_pk_mul_f32 v[132:133], v[76:77], v[108:109]
	v_mul_f32_e32 v127, v72, v127
	v_cvt_pk_bf16_f32 v108, v120, v121
	v_cvt_pk_bf16_f32 v109, v122, v123
	v_cvt_pk_bf16_f32 v110, v116, v117
	v_cvt_pk_bf16_f32 v111, v118, v119
	v_mov_b32_e32 v250, v143
	v_mov_b32_e32 v219, v143
	s_nop 1
	v_permlane16_swap_b32_e32 v250, v219
	v_cndmask_b32_e64 v118, v219, v250, s[100:101]
	v_mov_b32_e32 v250, v127
	v_mov_b32_e32 v219, v127
	s_nop 1
	v_permlane16_swap_b32_e32 v250, v219
	v_cndmask_b32_e64 v116, v219, v250, s[100:101]
	v_pk_mul_f32 v[112:113], v[112:113], v[136:137] op_sel_hi:[1,0]
	v_pk_mul_f32 v[114:115], v[114:115], v[136:137] op_sel_hi:[1,0]
	v_pk_mul_f32 v[112:113], v[84:85], v[112:113]
	v_pk_mul_f32 v[114:115], v[86:87], v[114:115]
	global_store_dwordx4 v[124:125], v[108:111], off
	v_mul_f32_e32 v144, v74, v144
	v_mul_f32_e32 v119, v137, v143
	v_cvt_pk_bf16_f32 v108, v112, v113
	v_cvt_pk_bf16_f32 v109, v114, v115
	v_cvt_pk_bf16_f32 v110, v132, v133
	v_cvt_pk_bf16_f32 v111, v128, v129
	global_store_dwordx4 v[124:125], v[108:111], off offset:64
	v_mul_f32_e32 v117, v141, v127
	v_mov_b32_e32 v250, v144
	v_mov_b32_e32 v219, v144
	s_nop 1
	v_permlane16_swap_b32_e32 v250, v219
	v_cndmask_b32_e64 v120, v219, v250, s[100:101]
	s_waitcnt lgkmcnt(2)
	v_cndmask_b32_e64 v109, v118, -v118, s[6:7]
	s_waitcnt lgkmcnt(1)
	v_cndmask_b32_e64 v108, v116, -v116, s[6:7]
	v_fmac_f32_e32 v119, v138, v109
	v_mul_f32_e32 v109, 0x3d0186e2, v126
	v_fmac_f32_e32 v117, v142, v108
	v_mul_f32_e32 v108, v75, v145
	v_mul_f32_e32 v109, 0.15915494, v109
	v_cos_f32_e32 v111, v109
	v_mov_b32_e32 v250, v108
	v_mov_b32_e32 v219, v108
	s_nop 1
	v_permlane16_swap_b32_e32 v250, v219
	v_cndmask_b32_e64 v112, v219, v250, s[100:101]
	v_mul_f32_e32 v121, v139, v144
	s_waitcnt lgkmcnt(1)
	v_cndmask_b32_e64 v110, v120, -v120, s[6:7]
	v_fmac_f32_e32 v121, v140, v110
	v_cndmask_b32_e64 v110, 1.0, v111, s[14:15]
	v_mul_f32_e32 v110, v110, v108
	s_waitcnt lgkmcnt(0)
	v_cndmask_b32_e64 v108, v112, -v112, s[6:7]
	v_mul_f32_e32 v112, 0x3c23d70a, v126
	v_sin_f32_e32 v109, v109
	v_mul_f32_e32 v111, v136, v135
	v_mul_f32_e32 v112, 0.15915494, v112
	v_mul_f32_e32 v111, v68, v111
	v_cos_f32_e32 v113, v112
	v_sin_f32_e32 v112, v112
	v_mov_b32_e32 v250, v111
	v_mov_b32_e32 v219, v111
	s_nop 1
	v_permlane16_swap_b32_e32 v250, v219
	v_cndmask_b32_e64 v114, v219, v250, s[100:101]
	v_cndmask_b32_e64 v109, 0, v109, s[14:15]
	v_fmac_f32_e32 v110, v109, v108
	v_cndmask_b32_e64 v108, 1.0, v113, s[14:15]
	v_mul_f32_e32 v113, 0x3b4f3e37, v126
	v_cndmask_b32_e64 v109, 0, v112, s[14:15]
	v_mul_f32_e32 v112, v136, v134
	v_mul_f32_e32 v113, 0.15915494, v113
	v_mul_f32_e32 v111, v108, v111
	s_waitcnt lgkmcnt(0)
	v_cndmask_b32_e64 v108, v114, -v114, s[6:7]
	v_mul_f32_e32 v112, v69, v112
	v_cos_f32_e32 v114, v113
	v_sin_f32_e32 v113, v113
	v_mov_b32_e32 v250, v112
	v_mov_b32_e32 v219, v112
	s_nop 1
	v_permlane16_swap_b32_e32 v250, v219
	v_cndmask_b32_e64 v115, v219, v250, s[100:101]
	v_fmac_f32_e32 v111, v109, v108
	v_cndmask_b32_e64 v108, 1.0, v114, s[14:15]
	v_mul_f32_e32 v114, 0x3a83126f, v126
	v_cndmask_b32_e64 v109, 0, v113, s[14:15]
	v_mul_f32_e32 v113, v136, v131
	v_mul_f32_e32 v114, 0.15915494, v114
	v_mul_f32_e32 v112, v108, v112
	s_waitcnt lgkmcnt(0)
	v_cndmask_b32_e64 v108, v115, -v115, s[6:7]
	v_mul_f32_e32 v113, v70, v113
	v_cos_f32_e32 v115, v114
	v_sin_f32_e32 v114, v114
	v_mov_b32_e32 v250, v113
	v_mov_b32_e32 v219, v113
	s_nop 1
	v_permlane16_swap_b32_e32 v250, v219
	v_cndmask_b32_e64 v116, v219, v250, s[100:101]
	v_fmac_f32_e32 v112, v109, v108
	v_cndmask_b32_e64 v108, 1.0, v115, s[14:15]
	v_cndmask_b32_e64 v109, 0, v114, s[14:15]
	v_mul_f32_e32 v114, v136, v130
	v_mul_f32_e32 v115, 0x39a5cb5f, v126
	v_mul_f32_e32 v114, v71, v114
	v_mul_f32_e32 v115, 0.15915494, v115
	v_mul_f32_e32 v113, v108, v113
	s_waitcnt lgkmcnt(0)
	v_cndmask_b32_e64 v108, v116, -v116, s[6:7]
	v_cos_f32_e32 v116, v115
	v_mov_b32_e32 v250, v114
	v_mov_b32_e32 v219, v114
	s_nop 1
	v_permlane16_swap_b32_e32 v250, v219
	v_cndmask_b32_e64 v118, v219, v250, s[100:101]
	v_sin_f32_e32 v115, v115
	v_fmac_f32_e32 v113, v109, v108
	v_cndmask_b32_e64 v108, 1.0, v116, s[14:15]
	v_mul_f32_e32 v114, v108, v114
	v_cndmask_b32_e64 v109, 0, v115, s[14:15]
	s_waitcnt lgkmcnt(0)
	v_cndmask_b32_e64 v108, v118, -v118, s[6:7]
	v_fmac_f32_e32 v114, v109, v108
	v_cvt_pk_bf16_f32 v108, v117, v119
	v_cvt_pk_bf16_f32 v109, v121, v110
	v_cvt_pk_bf16_f32 v110, v111, v112
	v_cvt_pk_bf16_f32 v111, v113, v114
	global_store_dwordx4 v[124:125], v[108:111], off offset:128
	s_nop 1
	v_mov_b32_e32 v110, v195
	s_and_saveexec_b64 s[34:35], s[8:9]
	s_cbranch_execz .LBB0_1514
	v_mov_b32_e32 v110, v204
	global_store_dwordx4 v[124:125], v[0:3], off offset:192
;     __device__ __forceinline__ void operator()(const f32x4 (&acc)[2][2][4][2], const Unit& u, int wr, int wc, int fr, int fq) const {
;     ...
;                     const u32x4 praw = *(const u32x4*)(KPE + (size_t)row * 32 + 8 * fq); float pe[8];
; #pragma unroll
;                     for (int e = 0; e < 4; ++e) { pe[2 * e] = __uint_as_float(praw[e] << 16); pe[2 * e + 1] = __uint_as_float(praw[e] & 0xffff0000u); }
;                     float ss = 0.f;
; #pragma unroll
;                     for (int bj = 0; bj < 2; ++bj)
; #pragma unroll
;                         for (int n = 0; n < 2; ++n) { const f32x4 v = acc[ai][bj][m][n]; ss += (v[0] * v[0] + v[1] * v[1]) + (v[2] * v[2] + v[3] * v[3]); }
; #pragma unroll
;                     for (int e = 0; e < 8; ++e) ss += pe[e] * pe[e];
;                     ss += __shfl_xor(ss, 16); ss += __shfl_xor(ss, 32);
;                     const float rstd = rsqrtf(ss * (1.0f / 96.0f) + EPS);
.LBB0_1514:
	s_or_b64 exec, exec, s[34:35]
	v_or_b32_e32 v108, 48, v182
	v_ashrrev_i32_e32 v109, 31, v108
	v_lshlrev_b64 v[108:109], 6, v[108:109]
	v_lshl_add_u64 v[108:109], v[168:169], 0, v[108:109]
	v_mov_b32_e32 v112, v228
	v_mov_b32_e32 v113, v229
	v_mov_b32_e32 v114, v230
	v_mov_b32_e32 v115, v231
	v_mul_f32_e32 v111, v105, v105
	v_mul_f32_e32 v116, v107, v107
	v_mul_f32_e32 v117, v101, v101
	v_mul_f32_e32 v118, v103, v103
	v_mul_f32_e32 v119, v97, v97
	v_mul_f32_e32 v120, v99, v99
	v_fmac_f32_e32 v111, v104, v104
	v_fmac_f32_e32 v116, v106, v106
	v_fmac_f32_e32 v117, v100, v100
	v_fmac_f32_e32 v118, v102, v102
	v_mul_f32_e32 v121, v93, v93
	v_mul_f32_e32 v122, v95, v95
	v_fmac_f32_e32 v119, v96, v96
	v_fmac_f32_e32 v120, v98, v98
	v_add_f32_e32 v111, v111, v116
	v_add_f32_e32 v116, v117, v118
	v_fmac_f32_e32 v121, v92, v92
	v_fmac_f32_e32 v122, v94, v94
	v_add_f32_e32 v117, v119, v120
	v_add_f32_e32 v111, v116, v111
	v_add_f32_e32 v118, v121, v122
	v_add_f32_e32 v111, v117, v111
	v_add_f32_e32 v111, v118, v111
	v_mul_f32_e32 v123, 0.15915494, v110
	v_cos_f32_e32 v128, v123
	v_sin_f32_e32 v129, v123
	v_mul_f32_e32 v124, 0x3ea1e89b, v110
	v_mul_f32_e32 v125, 0x3dcccccd, v110
	v_mul_f32_e32 v130, 0.15915494, v124
	v_mul_f32_e32 v131, 0.15915494, v125
	v_or_b32_e32 v164, 48, v184
	v_lshl_add_u64 v[108:109], s[4:5], 0, v[164:165]
	v_lshlrev_b64 v[108:109], 8, v[108:109]
	v_lshl_add_u64 v[108:109], v[172:173], 0, v[108:109]
	s_waitcnt vmcnt(0)
	v_and_b32_e32 v116, 0xffff0000, v112
	v_lshlrev_b32_e32 v117, 16, v112
	v_pk_mul_f32 v[120:121], v[116:117], v[116:117]
	v_and_b32_e32 v112, 0xffff0000, v113
	v_lshlrev_b32_e32 v113, 16, v113
	v_add_f32_e32 v111, v111, v121
	v_pk_mul_f32 v[122:123], v[112:113], v[112:113]
	v_add_f32_e32 v111, v120, v111
	v_and_b32_e32 v118, 0xffff0000, v114
	v_lshlrev_b32_e32 v119, 16, v114
	v_add_f32_e32 v111, v123, v111
	v_pk_mul_f32 v[124:125], v[118:119], v[118:119]
	v_add_f32_e32 v111, v122, v111
	v_and_b32_e32 v114, 0xffff0000, v115
	v_lshlrev_b32_e32 v115, 16, v115
	v_add_f32_e32 v111, v125, v111
	v_pk_mul_f32 v[126:127], v[114:115], v[114:115]
	v_add_f32_e32 v111, v124, v111
	v_add_f32_e32 v111, v127, v111
	v_add_f32_e32 v111, v126, v111
	v_mov_b32_e32 v250, v111
	v_mov_b32_e32 v219, v111
	s_nop 1
	v_permlane16_swap_b32_e32 v250, v219
	v_cndmask_b32_e64 v120, v219, v250, s[100:101]
	v_cos_f32_e32 v121, v130
	v_cndmask_b32_e64 v125, 1.0, v128, s[14:15]
	v_cndmask_b32_e64 v126, 0, v129, s[14:15]
	v_sin_f32_e32 v122, v130
	s_waitcnt lgkmcnt(0)
	v_add_f32_e32 v111, v111, v120
	ds_bpermute_b32 v120, v203, v111
	v_cndmask_b32_e64 v121, 1.0, v121, s[14:15]
	v_cndmask_b32_e64 v122, 0, v122, s[14:15]
	v_cos_f32_e32 v123, v131
	v_sin_f32_e32 v124, v131
	s_waitcnt lgkmcnt(0)
	v_add_f32_e32 v111, v111, v120
	v_fmamk_f32 v111, v111, 0x3c2aaaab, v199
	v_mul_f32_e32 v120, 0x4b800000, v111
	v_cmp_gt_f32_e32 vcc, s69, v111
	v_cndmask_b32_e64 v123, 1.0, v123, s[14:15]
	v_cndmask_b32_e64 v124, 0, v124, s[14:15]
	v_cndmask_b32_e32 v111, v111, v120, vcc
	v_rsq_f32_e32 v111, v111
	s_nop 0
	v_mul_f32_e32 v120, 0x45800000, v111
	v_cndmask_b32_e32 v120, v111, v120, vcc
	v_pk_mul_f32 v[102:103], v[102:103], v[120:121] op_sel_hi:[1,0]
	v_mul_f32_e32 v127, v120, v116
	v_pk_mul_f32 v[104:105], v[104:105], v[120:121] op_sel_hi:[1,0]
	v_pk_mul_f32 v[106:107], v[106:107], v[120:121] op_sel_hi:[1,0]
	v_pk_mul_f32 v[100:101], v[100:101], v[120:121] op_sel_hi:[1,0]
	v_pk_mul_f32 v[92:93], v[92:93], v[120:121] op_sel_hi:[1,0]
	v_pk_mul_f32 v[94:95], v[94:95], v[120:121] op_sel_hi:[1,0]
	v_mul_f32_e32 v111, v120, v117
	v_pk_mul_f32 v[102:103], v[82:83], v[102:103]
	v_mul_f32_e32 v127, v73, v127
	v_mul_f32_e32 v128, v120, v113
	v_mul_f32_e32 v129, v120, v112
	v_pk_mul_f32 v[106:107], v[90:91], v[106:107]
	v_pk_mul_f32 v[104:105], v[88:89], v[104:105]
	v_pk_mul_f32 v[100:101], v[80:81], v[100:101]
	v_pk_mul_f32 v[112:113], v[78:79], v[94:95]
	v_pk_mul_f32 v[116:117], v[76:77], v[92:93]
	v_mul_f32_e32 v111, v72, v111
	v_cvt_pk_bf16_f32 v92, v104, v105
	v_cvt_pk_bf16_f32 v93, v106, v107
	v_cvt_pk_bf16_f32 v94, v100, v101
	v_cvt_pk_bf16_f32 v95, v102, v103
	v_mov_b32_e32 v250, v127
	v_mov_b32_e32 v219, v127
	s_nop 1
	v_permlane16_swap_b32_e32 v250, v219
	v_cndmask_b32_e64 v102, v219, v250, s[100:101]
	v_mov_b32_e32 v250, v111
	v_mov_b32_e32 v219, v111
	s_nop 1
	v_permlane16_swap_b32_e32 v250, v219
	v_cndmask_b32_e64 v100, v219, v250, s[100:101]
	v_pk_mul_f32 v[96:97], v[96:97], v[120:121] op_sel_hi:[1,0]
	v_pk_mul_f32 v[98:99], v[98:99], v[120:121] op_sel_hi:[1,0]
	v_pk_mul_f32 v[96:97], v[84:85], v[96:97]
	v_pk_mul_f32 v[98:99], v[86:87], v[98:99]
	global_store_dwordx4 v[108:109], v[92:95], off
	v_mul_f32_e32 v128, v74, v128
	v_mul_f32_e32 v103, v121, v127
	v_cvt_pk_bf16_f32 v92, v96, v97
	v_cvt_pk_bf16_f32 v93, v98, v99
	v_cvt_pk_bf16_f32 v94, v116, v117
	v_cvt_pk_bf16_f32 v95, v112, v113
	global_store_dwordx4 v[108:109], v[92:95], off offset:64
	v_mul_f32_e32 v101, v125, v111
	v_mov_b32_e32 v250, v128
	v_mov_b32_e32 v219, v128
	s_nop 1
	v_permlane16_swap_b32_e32 v250, v219
	v_cndmask_b32_e64 v104, v219, v250, s[100:101]
	s_waitcnt lgkmcnt(2)
	v_cndmask_b32_e64 v93, v102, -v102, s[6:7]
	s_waitcnt lgkmcnt(1)
	v_cndmask_b32_e64 v92, v100, -v100, s[6:7]
	v_fmac_f32_e32 v103, v122, v93
	v_mul_f32_e32 v93, 0x3d0186e2, v110
	v_fmac_f32_e32 v101, v126, v92
	v_mul_f32_e32 v92, v75, v129
	v_mul_f32_e32 v93, 0.15915494, v93
	v_cos_f32_e32 v95, v93
	v_mov_b32_e32 v250, v92
	v_mov_b32_e32 v219, v92
	s_nop 1
	v_permlane16_swap_b32_e32 v250, v219
	v_cndmask_b32_e64 v96, v219, v250, s[100:101]
	v_mul_f32_e32 v105, v123, v128
	s_waitcnt lgkmcnt(1)
; __device__ __forceinline__ u32x4 pack8(f32x4 v0, f32x4 v1) { u32x4 w; w.x = cvt_pk_bf16(v0[0], v0[1]); w.y = cvt_pk_bf16(v0[2], v0[3]); w.z = cvt_pk_bf16(v1[0], v1[1]); w.w = cvt_pk_bf16(v1[2], v1[3]); return w; }
;     __device__ __forceinline__ void operator()(const f32x4 (&acc)[2][2][4][2], const Unit& u, int wr, int wc, int fr, int fq) const {
;     ...
;                     const u32x4 praw = *(const u32x4*)(KPE + (size_t)row * 32 + 8 * fq); float pe[8];
; #pragma unroll
;                     for (int e = 0; e < 4; ++e) { pe[2 * e] = __uint_as_float(praw[e] << 16); pe[2 * e + 1] = __uint_as_float(praw[e] & 0xffff0000u); }
;                     float ss = 0.f;
; #pragma unroll
;                     for (int bj = 0; bj < 2; ++bj)
; #pragma unroll
;                         for (int n = 0; n < 2; ++n) { const f32x4 v = acc[ai][bj][m][n]; ss += (v[0] * v[0] + v[1] * v[1]) + (v[2] * v[2] + v[3] * v[3]); }
; #pragma unroll
;                     for (int e = 0; e < 8; ++e) ss += pe[e] * pe[e];
;                     ss += __shfl_xor(ss, 16); ss += __shfl_xor(ss, 32);
;                     const float rstd = rsqrtf(ss * (1.0f / 96.0f) + EPS);
;                     bf16_t* kd = KH + ((size_t)(b * NHEAD + h) * SPB + sp) * 128;
; #pragma unroll
;                     for (int bj = 0; bj < 2; ++bj) *(u32x4*)(kd + 32 * bj + 8 * fq) = pack8(acc[ai][bj][m][0] * rstd * g0[bj], acc[ai][bj][m][1] * rstd * g1[bj]);
;                     const int l = sp - CTXL; const float pos = (fq >> 1) ? (float)(l & 63) : (float)(l >> 6);
;                     f32x4 o0, o1;
; #pragma unroll
;                     for (int e = 0; e < 8; ++e) { const float own = pe[e] * rstd * (e < 4 ? gp0[e & 3] : gp1[e & 3]); const float other = __shfl_xor(own, 16);
;                         float cs = 1.f, sn = 0.f; if (lat) { const float ang = pos * invf[e]; cs = __cosf(ang); sn = __sinf(ang); }
;                         const float r = own * cs + sgn * other * sn; if (e < 4) o0[e & 3] = r; else o1[e & 3] = r; }
;                     *(u32x4*)(kd + 64 + 8 * fq) = pack8(o0, o1);
;                     if (fq < 2) *(u32x4*)(kd + 96 + 8 * fq) = (u32x4){fq == 0 ? 0x3F80u : 0u, 0u, 0u, 0u};
	v_cndmask_b32_e64 v94, v104, -v104, s[6:7]
	v_fmac_f32_e32 v105, v124, v94
	v_cndmask_b32_e64 v94, 1.0, v95, s[14:15]
	v_mul_f32_e32 v94, v94, v92
	s_waitcnt lgkmcnt(0)
	v_cndmask_b32_e64 v92, v96, -v96, s[6:7]
	v_mul_f32_e32 v96, 0x3c23d70a, v110
	v_sin_f32_e32 v93, v93
	v_mul_f32_e32 v95, v120, v119
	v_mul_f32_e32 v96, 0.15915494, v96
	v_mul_f32_e32 v95, v68, v95
	v_cos_f32_e32 v97, v96
	v_sin_f32_e32 v96, v96
	v_mov_b32_e32 v250, v95
	v_mov_b32_e32 v219, v95
	s_nop 1
	v_permlane16_swap_b32_e32 v250, v219
	v_cndmask_b32_e64 v98, v219, v250, s[100:101]
	v_cndmask_b32_e64 v93, 0, v93, s[14:15]
	v_fmac_f32_e32 v94, v93, v92
	v_cndmask_b32_e64 v92, 1.0, v97, s[14:15]
	v_mul_f32_e32 v97, 0x3b4f3e37, v110
	v_cndmask_b32_e64 v93, 0, v96, s[14:15]
	v_mul_f32_e32 v96, v120, v118
	v_mul_f32_e32 v97, 0.15915494, v97
	v_mul_f32_e32 v95, v92, v95
	s_waitcnt lgkmcnt(0)
	v_cndmask_b32_e64 v92, v98, -v98, s[6:7]
	v_mul_f32_e32 v96, v69, v96
	v_cos_f32_e32 v98, v97
	v_sin_f32_e32 v97, v97
	v_mov_b32_e32 v250, v96
	v_mov_b32_e32 v219, v96
	s_nop 1
	v_permlane16_swap_b32_e32 v250, v219
	v_cndmask_b32_e64 v99, v219, v250, s[100:101]
	v_fmac_f32_e32 v95, v93, v92
	v_cndmask_b32_e64 v92, 1.0, v98, s[14:15]
	v_mul_f32_e32 v98, 0x3a83126f, v110
	v_cndmask_b32_e64 v93, 0, v97, s[14:15]
	v_mul_f32_e32 v97, v120, v115
	v_mul_f32_e32 v98, 0.15915494, v98
	v_mul_f32_e32 v96, v92, v96
	s_waitcnt lgkmcnt(0)
	v_cndmask_b32_e64 v92, v99, -v99, s[6:7]
	v_mul_f32_e32 v97, v70, v97
	v_cos_f32_e32 v99, v98
	v_sin_f32_e32 v98, v98
	v_mov_b32_e32 v250, v97
	v_mov_b32_e32 v219, v97
	s_nop 1
	v_permlane16_swap_b32_e32 v250, v219
	v_cndmask_b32_e64 v100, v219, v250, s[100:101]
	v_fmac_f32_e32 v96, v93, v92
	v_cndmask_b32_e64 v92, 1.0, v99, s[14:15]
	v_cndmask_b32_e64 v93, 0, v98, s[14:15]
	v_mul_f32_e32 v98, v120, v114
	v_mul_f32_e32 v99, 0x39a5cb5f, v110
	v_mul_f32_e32 v98, v71, v98
	v_mul_f32_e32 v99, 0.15915494, v99
	v_mul_f32_e32 v97, v92, v97
	s_waitcnt lgkmcnt(0)
	v_cndmask_b32_e64 v92, v100, -v100, s[6:7]
	v_cos_f32_e32 v100, v99
	v_mov_b32_e32 v250, v98
	v_mov_b32_e32 v219, v98
	s_nop 1
	v_permlane16_swap_b32_e32 v250, v219
	v_cndmask_b32_e64 v102, v219, v250, s[100:101]
	v_sin_f32_e32 v99, v99
	v_fmac_f32_e32 v97, v93, v92
	v_cndmask_b32_e64 v92, 1.0, v100, s[14:15]
	v_mul_f32_e32 v98, v92, v98
	v_cndmask_b32_e64 v93, 0, v99, s[14:15]
	s_waitcnt lgkmcnt(0)
	v_cndmask_b32_e64 v92, v102, -v102, s[6:7]
	v_fmac_f32_e32 v98, v93, v92
	v_cvt_pk_bf16_f32 v92, v101, v103
	v_cvt_pk_bf16_f32 v93, v105, v94
	v_cvt_pk_bf16_f32 v94, v95, v96
	v_cvt_pk_bf16_f32 v95, v97, v98
	global_store_dwordx4 v[108:109], v[92:95], off offset:128
	s_and_saveexec_b64 s[34:35], s[8:9]
	s_cbranch_execz .LBB0_1516
	global_store_dwordx4 v[108:109], v[0:3], off offset:192
.LBB0_1516:
	s_or_b64 exec, exec, s[34:35]
	v_lshlrev_b64 v[92:93], 6, v[182:183]
	v_lshl_add_u64 v[92:93], v[168:169], 0, v[92:93]
	v_add_co_u32_e32 v94, vcc, 0x2000, v92
	v_mul_f32_e32 v97, v65, v65
	s_nop 0
	v_addc_co_u32_e32 v95, vcc, 0, v93, vcc
	v_mov_b32_e32 v98, v232
	v_mov_b32_e32 v99, v233
	v_mov_b32_e32 v100, v234
	v_mov_b32_e32 v101, v235
	v_mul_f32_e32 v102, v67, v67
	v_mul_f32_e32 v103, v61, v61
	v_mul_f32_e32 v104, v63, v63
	v_mul_f32_e32 v105, v57, v57
	v_mul_f32_e32 v106, v59, v59
	v_fmac_f32_e32 v97, v64, v64
	v_fmac_f32_e32 v102, v66, v66
	v_fmac_f32_e32 v103, v60, v60
	v_fmac_f32_e32 v104, v62, v62
	v_mul_f32_e32 v107, v53, v53
	v_mul_f32_e32 v108, v55, v55
	v_fmac_f32_e32 v105, v56, v56
	v_fmac_f32_e32 v106, v58, v58
	v_add_f32_e32 v97, v97, v102
	v_add_f32_e32 v102, v103, v104
	v_fmac_f32_e32 v107, v52, v52
	v_fmac_f32_e32 v108, v54, v54
	v_add_f32_e32 v103, v105, v106
	v_add_f32_e32 v97, v102, v97
	v_add_f32_e32 v104, v107, v108
	v_add_f32_e32 v97, v103, v97
	v_add_f32_e32 v97, v104, v97
	s_addk_i32 s27, 0xff80
	s_ashr_i32 s27, s27, 6
	v_cvt_f32_i32_e32 v96, s27
	v_add_u32_e32 v164, 0x80, v184
	v_lshl_add_u64 v[94:95], s[4:5], 0, v[164:165]
	v_lshlrev_b64 v[94:95], 8, v[94:95]
	v_cndmask_b32_e64 v114, v192, v96, s[8:9]
	v_mul_f32_e32 v115, 0.15915494, v114
	v_mul_f32_e32 v116, 0x3ea1e89b, v114
	v_mul_f32_e32 v117, 0x3dcccccd, v114
	v_cos_f32_e32 v118, v115
	v_lshl_add_u64 v[94:95], v[172:173], 0, v[94:95]
	s_waitcnt vmcnt(0)
	v_and_b32_e32 v102, 0xffff0000, v98
	v_lshlrev_b32_e32 v103, 16, v98
	v_pk_mul_f32 v[106:107], v[102:103], v[102:103]
	v_and_b32_e32 v98, 0xffff0000, v99
	v_lshlrev_b32_e32 v99, 16, v99
	v_add_f32_e32 v97, v97, v107
	v_pk_mul_f32 v[108:109], v[98:99], v[98:99]
	v_add_f32_e32 v97, v106, v97
	v_and_b32_e32 v104, 0xffff0000, v100
	v_lshlrev_b32_e32 v105, 16, v100
	v_add_f32_e32 v97, v109, v97
	v_pk_mul_f32 v[110:111], v[104:105], v[104:105]
	v_add_f32_e32 v97, v108, v97
	v_and_b32_e32 v100, 0xffff0000, v101
	v_lshlrev_b32_e32 v101, 16, v101
	v_add_f32_e32 v97, v111, v97
	v_pk_mul_f32 v[112:113], v[100:101], v[100:101]
	v_add_f32_e32 v97, v110, v97
	v_add_f32_e32 v97, v113, v97
	v_add_f32_e32 v97, v112, v97
	v_mov_b32_e32 v250, v97
	v_mov_b32_e32 v219, v97
	s_nop 1
	v_permlane16_swap_b32_e32 v250, v219
	v_cndmask_b32_e64 v106, v219, v250, s[100:101]
	v_sin_f32_e32 v107, v115
	v_mul_f32_e32 v108, 0.15915494, v116
	v_cos_f32_e32 v110, v108
	v_sin_f32_e32 v108, v108
	s_waitcnt lgkmcnt(0)
	v_add_f32_e32 v97, v97, v106
	ds_bpermute_b32 v106, v203, v97
	v_cndmask_b32_e64 v107, 0, v107, s[14:15]
	v_mul_f32_e32 v109, 0.15915494, v117
	v_cos_f32_e32 v111, v109
	v_sin_f32_e32 v112, v109
	s_waitcnt lgkmcnt(0)
; __device__ __forceinline__ u32x4 pack8(f32x4 v0, f32x4 v1) { u32x4 w; w.x = cvt_pk_bf16(v0[0], v0[1]); w.y = cvt_pk_bf16(v0[2], v0[3]); w.z = cvt_pk_bf16(v1[0], v1[1]); w.w = cvt_pk_bf16(v1[2], v1[3]); return w; }
;     __device__ __forceinline__ void operator()(const f32x4 (&acc)[2][2][4][2], const Unit& u, int wr, int wc, int fr, int fq) const {
;     ...
;                     ss += __shfl_xor(ss, 16); ss += __shfl_xor(ss, 32);
;                     const float rstd = rsqrtf(ss * (1.0f / 96.0f) + EPS);
;                     bf16_t* kd = KH + ((size_t)(b * NHEAD + h) * SPB + sp) * 128;
; #pragma unroll
;                     for (int bj = 0; bj < 2; ++bj) *(u32x4*)(kd + 32 * bj + 8 * fq) = pack8(acc[ai][bj][m][0] * rstd * g0[bj], acc[ai][bj][m][1] * rstd * g1[bj]);
;                     const int l = sp - CTXL; const float pos = (fq >> 1) ? (float)(l & 63) : (float)(l >> 6);
;                     f32x4 o0, o1;
; #pragma unroll
;                     for (int e = 0; e < 8; ++e) { const float own = pe[e] * rstd * (e < 4 ? gp0[e & 3] : gp1[e & 3]); const float other = __shfl_xor(own, 16);
;                         float cs = 1.f, sn = 0.f; if (lat) { const float ang = pos * invf[e]; cs = __cosf(ang); sn = __sinf(ang); }
;                         const float r = own * cs + sgn * other * sn; if (e < 4) o0[e & 3] = r; else o1[e & 3] = r; }
;                     *(u32x4*)(kd + 64 + 8 * fq) = pack8(o0, o1);
;                     if (fq < 2) *(u32x4*)(kd + 96 + 8 * fq) = (u32x4){fq == 0 ? 0x3F80u : 0u, 0u, 0u, 0u};
	v_add_f32_e32 v97, v97, v106
	v_fmamk_f32 v97, v97, 0x3c2aaaab, v199
	v_mul_f32_e32 v106, 0x4b800000, v97
	v_cmp_gt_f32_e32 vcc, s69, v97
	v_cndmask_b32_e64 v115, 0, v108, s[14:15]
	v_cndmask_b32_e64 v113, 1.0, v118, s[14:15]
	v_cndmask_b32_e32 v97, v97, v106, vcc
	v_rsq_f32_e32 v97, v97
	v_cndmask_b32_e64 v110, 1.0, v110, s[14:15]
	v_mul_f32_e32 v106, 0x45800000, v97
	v_cndmask_b32_e32 v106, v97, v106, vcc
	v_pk_mul_f32 v[60:61], v[60:61], v[106:107] op_sel_hi:[1,0]
	v_mul_f32_e32 v97, v106, v103
	v_pk_mul_f32 v[64:65], v[64:65], v[106:107] op_sel_hi:[1,0]
	v_pk_mul_f32 v[66:67], v[66:67], v[106:107] op_sel_hi:[1,0]
	v_pk_mul_f32 v[52:53], v[52:53], v[106:107] op_sel_hi:[1,0]
	v_pk_mul_f32 v[54:55], v[54:55], v[106:107] op_sel_hi:[1,0]
	v_pk_mul_f32 v[60:61], v[80:81], v[60:61]
	v_mul_f32_e32 v97, v72, v97
	v_mul_f32_e32 v116, v106, v102
	v_pk_mul_f32 v[66:67], v[90:91], v[66:67]
	v_pk_mul_f32 v[64:65], v[88:89], v[64:65]
	v_pk_mul_f32 v[102:103], v[78:79], v[54:55]
	v_pk_mul_f32 v[108:109], v[76:77], v[52:53]
	v_cvt_pk_bf16_f32 v52, v64, v65
	v_cvt_pk_bf16_f32 v53, v66, v67
	v_cvt_pk_bf16_f32 v54, v60, v61
	v_mov_b32_e32 v250, v97
	v_mov_b32_e32 v219, v97
	s_nop 1
	v_permlane16_swap_b32_e32 v250, v219
	v_cndmask_b32_e64 v60, v219, v250, s[100:101]
	v_pk_mul_f32 v[62:63], v[62:63], v[106:107] op_sel_hi:[1,0]
	v_pk_mul_f32 v[56:57], v[56:57], v[106:107] op_sel_hi:[1,0]
	v_pk_mul_f32 v[62:63], v[82:83], v[62:63]
	v_mul_f32_e32 v116, v73, v116
	v_pk_mul_f32 v[58:59], v[58:59], v[106:107] op_sel_hi:[1,0]
	v_mul_f32_e32 v99, v106, v99
	v_pk_mul_f32 v[56:57], v[84:85], v[56:57]
	v_cvt_pk_bf16_f32 v55, v62, v63
	v_mov_b32_e32 v250, v116
	v_mov_b32_e32 v219, v116
	s_nop 1
	v_permlane16_swap_b32_e32 v250, v219
	v_cndmask_b32_e64 v62, v219, v250, s[100:101]
	global_store_dwordx4 v[94:95], v[52:55], off
	v_pk_mul_f32 v[58:59], v[86:87], v[58:59]
	v_mul_f32_e32 v99, v74, v99
	v_cvt_pk_bf16_f32 v52, v56, v57
	v_mul_f32_e32 v61, v113, v97
	v_cvt_pk_bf16_f32 v53, v58, v59
	v_cvt_pk_bf16_f32 v54, v108, v109
	v_cvt_pk_bf16_f32 v55, v102, v103
	global_store_dwordx4 v[94:95], v[52:55], off offset:64
	v_mul_f32_e32 v56, 0x3d0186e2, v114
	v_mul_f32_e32 v56, 0.15915494, v56
	s_waitcnt lgkmcnt(1)
	v_cndmask_b32_e64 v52, v60, -v60, s[6:7]
	v_fmac_f32_e32 v61, v107, v52
	v_mov_b32_e32 v250, v99
	v_mov_b32_e32 v219, v99
	s_nop 1
	v_permlane16_swap_b32_e32 v250, v219
	v_cndmask_b32_e64 v52, v219, v250, s[100:101]
	v_mul_f32_e32 v55, v106, v98
	v_mul_f32_e32 v55, v75, v55
	v_cos_f32_e32 v57, v56
	v_mul_f32_e32 v63, v110, v116
	s_waitcnt lgkmcnt(1)
	v_cndmask_b32_e64 v53, v62, -v62, s[6:7]
	v_sin_f32_e32 v56, v56
	v_mov_b32_e32 v250, v55
	v_mov_b32_e32 v219, v55
	s_nop 1
	v_permlane16_swap_b32_e32 v250, v219
	v_cndmask_b32_e64 v58, v219, v250, s[100:101]
	v_fmac_f32_e32 v63, v115, v53
	v_cndmask_b32_e64 v53, 1.0, v111, s[14:15]
	v_cndmask_b32_e64 v54, 0, v112, s[14:15]
	v_mul_f32_e32 v53, v53, v99
	s_waitcnt lgkmcnt(1)
	v_cndmask_b32_e64 v52, v52, -v52, s[6:7]
	v_fmac_f32_e32 v53, v54, v52
	v_cndmask_b32_e64 v52, 1.0, v57, s[14:15]
	v_mul_f32_e32 v57, 0x3c23d70a, v114
	v_cndmask_b32_e64 v54, 0, v56, s[14:15]
	v_mul_f32_e32 v56, v106, v105
	v_mul_f32_e32 v57, 0.15915494, v57
	v_mul_f32_e32 v55, v52, v55
	s_waitcnt lgkmcnt(0)
	v_cndmask_b32_e64 v52, v58, -v58, s[6:7]
	v_mul_f32_e32 v56, v68, v56
	v_cos_f32_e32 v58, v57
	v_sin_f32_e32 v57, v57
	v_mov_b32_e32 v250, v56
	v_mov_b32_e32 v219, v56
	s_nop 1
	v_permlane16_swap_b32_e32 v250, v219
	v_cndmask_b32_e64 v59, v219, v250, s[100:101]
	v_fmac_f32_e32 v55, v54, v52
	v_cndmask_b32_e64 v52, 1.0, v58, s[14:15]
	v_mul_f32_e32 v58, 0x3b4f3e37, v114
	v_cndmask_b32_e64 v54, 0, v57, s[14:15]
	v_mul_f32_e32 v57, v106, v104
	v_mul_f32_e32 v58, 0.15915494, v58
	v_mul_f32_e32 v56, v52, v56
	s_waitcnt lgkmcnt(0)
	v_cndmask_b32_e64 v52, v59, -v59, s[6:7]
	v_mul_f32_e32 v57, v69, v57
	v_cos_f32_e32 v59, v58
	v_sin_f32_e32 v58, v58
	v_mov_b32_e32 v250, v57
	v_mov_b32_e32 v219, v57
	s_nop 1
	v_permlane16_swap_b32_e32 v250, v219
	v_cndmask_b32_e64 v60, v219, v250, s[100:101]
	v_fmac_f32_e32 v56, v54, v52
	v_cndmask_b32_e64 v52, 1.0, v59, s[14:15]
	v_mul_f32_e32 v59, 0x3a83126f, v114
	v_cndmask_b32_e64 v54, 0, v58, s[14:15]
	v_mul_f32_e32 v58, v106, v101
	v_mul_f32_e32 v59, 0.15915494, v59
	v_mul_f32_e32 v57, v52, v57
	s_waitcnt lgkmcnt(0)
	v_cndmask_b32_e64 v52, v60, -v60, s[6:7]
	v_mul_f32_e32 v58, v70, v58
	v_cos_f32_e32 v60, v59
	v_sin_f32_e32 v59, v59
	v_mov_b32_e32 v250, v58
	v_mov_b32_e32 v219, v58
	s_nop 1
	v_permlane16_swap_b32_e32 v250, v219
	v_cndmask_b32_e64 v62, v219, v250, s[100:101]
	v_fmac_f32_e32 v57, v54, v52
	v_cndmask_b32_e64 v52, 1.0, v60, s[14:15]
	v_cndmask_b32_e64 v54, 0, v59, s[14:15]
	v_mul_f32_e32 v59, v106, v100
	v_mul_f32_e32 v60, 0x39a5cb5f, v114
	v_mul_f32_e32 v59, v71, v59
	v_mul_f32_e32 v60, 0.15915494, v60
	v_mul_f32_e32 v58, v52, v58
	s_waitcnt lgkmcnt(0)
	v_cndmask_b32_e64 v52, v62, -v62, s[6:7]
	v_cos_f32_e32 v62, v60
	v_mov_b32_e32 v250, v59
	v_mov_b32_e32 v219, v59
	s_nop 1
	v_permlane16_swap_b32_e32 v250, v219
	v_cndmask_b32_e64 v64, v219, v250, s[100:101]
	v_sin_f32_e32 v60, v60
	v_fmac_f32_e32 v58, v54, v52
	v_cndmask_b32_e64 v52, 1.0, v62, s[14:15]
	v_mul_f32_e32 v59, v52, v59
	v_cndmask_b32_e64 v54, 0, v60, s[14:15]
	s_waitcnt lgkmcnt(0)
	v_cndmask_b32_e64 v52, v64, -v64, s[6:7]
	v_fmac_f32_e32 v59, v54, v52
	v_cvt_pk_bf16_f32 v52, v61, v63
	v_cvt_pk_bf16_f32 v53, v53, v55
	v_cvt_pk_bf16_f32 v54, v56, v57
	v_cvt_pk_bf16_f32 v55, v58, v59
	global_store_dwordx4 v[94:95], v[52:55], off offset:128
	s_nop 1
	v_mov_b32_e32 v54, v193
	s_and_saveexec_b64 s[34:35], s[8:9]
	s_cbranch_execz .LBB0_1518
	v_mov_b32_e32 v54, v96
	global_store_dwordx4 v[94:95], v[0:3], off offset:192
; __device__ __forceinline__ u32x4 pack8(f32x4 v0, f32x4 v1) { u32x4 w; w.x = cvt_pk_bf16(v0[0], v0[1]); w.y = cvt_pk_bf16(v0[2], v0[3]); w.z = cvt_pk_bf16(v1[0], v1[1]); w.w = cvt_pk_bf16(v1[2], v1[3]); return w; }
;     __device__ __forceinline__ void operator()(const f32x4 (&acc)[2][2][4][2], const Unit& u, int wr, int wc, int fr, int fq) const {
;     ...
;                     const u32x4 praw = *(const u32x4*)(KPE + (size_t)row * 32 + 8 * fq); float pe[8];
; #pragma unroll
;                     for (int e = 0; e < 4; ++e) { pe[2 * e] = __uint_as_float(praw[e] << 16); pe[2 * e + 1] = __uint_as_float(praw[e] & 0xffff0000u); }
;                     float ss = 0.f;
; #pragma unroll
;                     for (int bj = 0; bj < 2; ++bj)
; #pragma unroll
;                         for (int n = 0; n < 2; ++n) { const f32x4 v = acc[ai][bj][m][n]; ss += (v[0] * v[0] + v[1] * v[1]) + (v[2] * v[2] + v[3] * v[3]); }
; #pragma unroll
;                     for (int e = 0; e < 8; ++e) ss += pe[e] * pe[e];
;                     ss += __shfl_xor(ss, 16); ss += __shfl_xor(ss, 32);
;                     const float rstd = rsqrtf(ss * (1.0f / 96.0f) + EPS);
;                     bf16_t* kd = KH + ((size_t)(b * NHEAD + h) * SPB + sp) * 128;
; #pragma unroll
;                     for (int bj = 0; bj < 2; ++bj) *(u32x4*)(kd + 32 * bj + 8 * fq) = pack8(acc[ai][bj][m][0] * rstd * g0[bj], acc[ai][bj][m][1] * rstd * g1[bj]);
.LBB0_1518:
	s_or_b64 exec, exec, s[34:35]
	v_add_co_u32_e32 v52, vcc, 0x2000, v92
	v_mul_f32_e32 v55, v49, v49
	s_nop 0
	v_addc_co_u32_e32 v53, vcc, 0, v93, vcc
	v_mov_b32_e32 v56, v236
	v_mov_b32_e32 v57, v237
	v_mov_b32_e32 v58, v238
	v_mov_b32_e32 v59, v239
	v_mul_f32_e32 v60, v51, v51
	v_mul_f32_e32 v61, v45, v45
	v_mul_f32_e32 v62, v47, v47
	v_mul_f32_e32 v63, v41, v41
	v_mul_f32_e32 v64, v43, v43
	v_fmac_f32_e32 v55, v48, v48
	v_fmac_f32_e32 v60, v50, v50
	v_fmac_f32_e32 v61, v44, v44
	v_fmac_f32_e32 v62, v46, v46
	v_mul_f32_e32 v65, v37, v37
	v_mul_f32_e32 v66, v39, v39
	v_fmac_f32_e32 v63, v40, v40
	v_fmac_f32_e32 v64, v42, v42
	v_add_f32_e32 v55, v55, v60
	v_add_f32_e32 v60, v61, v62
	v_fmac_f32_e32 v65, v36, v36
	v_fmac_f32_e32 v66, v38, v38
	v_add_f32_e32 v61, v63, v64
	v_add_f32_e32 v55, v60, v55
	v_add_f32_e32 v62, v65, v66
	v_add_f32_e32 v55, v61, v55
	v_add_f32_e32 v55, v62, v55
	v_mul_f32_e32 v67, 0.15915494, v54
	v_cos_f32_e32 v97, v67
	v_sin_f32_e32 v98, v67
	v_mul_f32_e32 v92, 0x3ea1e89b, v54
	v_mul_f32_e32 v93, 0x3dcccccd, v54
	v_mul_f32_e32 v99, 0.15915494, v92
	v_mul_f32_e32 v100, 0.15915494, v93
	v_or_b32_e32 v52, 16, v164
	v_mov_b32_e32 v53, v165
	v_lshl_add_u64 v[52:53], s[4:5], 0, v[52:53]
	v_lshlrev_b64 v[52:53], 8, v[52:53]
	v_lshl_add_u64 v[52:53], v[172:173], 0, v[52:53]
	s_waitcnt vmcnt(0)
	v_and_b32_e32 v60, 0xffff0000, v56
	v_lshlrev_b32_e32 v61, 16, v56
	v_pk_mul_f32 v[64:65], v[60:61], v[60:61]
	v_and_b32_e32 v56, 0xffff0000, v57
	v_lshlrev_b32_e32 v57, 16, v57
	v_add_f32_e32 v55, v55, v65
	v_pk_mul_f32 v[66:67], v[56:57], v[56:57]
	v_add_f32_e32 v55, v64, v55
	v_and_b32_e32 v62, 0xffff0000, v58
	v_lshlrev_b32_e32 v63, 16, v58
	v_add_f32_e32 v55, v67, v55
	v_pk_mul_f32 v[92:93], v[62:63], v[62:63]
	v_add_f32_e32 v55, v66, v55
	v_and_b32_e32 v58, 0xffff0000, v59
	v_lshlrev_b32_e32 v59, 16, v59
	v_add_f32_e32 v55, v93, v55
	v_pk_mul_f32 v[94:95], v[58:59], v[58:59]
	v_add_f32_e32 v55, v92, v55
	v_add_f32_e32 v55, v95, v55
	v_add_f32_e32 v55, v94, v55
	v_mov_b32_e32 v250, v55
	v_mov_b32_e32 v219, v55
	s_nop 1
	v_permlane16_swap_b32_e32 v250, v219
	v_cndmask_b32_e64 v64, v219, v250, s[100:101]
	v_cos_f32_e32 v65, v99
	v_sin_f32_e32 v66, v99
	v_cos_f32_e32 v67, v100
	v_cndmask_b32_e64 v94, 0, v98, s[14:15]
	s_waitcnt lgkmcnt(0)
	v_add_f32_e32 v55, v55, v64
	ds_bpermute_b32 v64, v203, v55
	v_cndmask_b32_e64 v65, 1.0, v65, s[14:15]
	v_cndmask_b32_e64 v93, 1.0, v97, s[14:15]
	v_cndmask_b32_e64 v95, 0, v66, s[14:15]
	v_cndmask_b32_e64 v97, 1.0, v67, s[14:15]
	s_waitcnt lgkmcnt(0)
	v_add_f32_e32 v55, v55, v64
	v_fmamk_f32 v55, v55, 0x3c2aaaab, v199
	v_mul_f32_e32 v64, 0x4b800000, v55
	v_cmp_gt_f32_e32 vcc, s69, v55
	v_sin_f32_e32 v92, v100
	s_nop 0
	v_cndmask_b32_e32 v55, v55, v64, vcc
	v_rsq_f32_e32 v55, v55
	s_nop 0
	v_mul_f32_e32 v64, 0x45800000, v55
	v_cndmask_b32_e32 v64, v55, v64, vcc
	v_pk_mul_f32 v[44:45], v[44:45], v[64:65] op_sel_hi:[1,0]
	v_pk_mul_f32 v[46:47], v[46:47], v[64:65] op_sel_hi:[1,0]
	v_mul_f32_e32 v55, v64, v61
	v_mul_f32_e32 v98, v64, v60
	v_pk_mul_f32 v[48:49], v[48:49], v[64:65] op_sel_hi:[1,0]
	v_pk_mul_f32 v[50:51], v[50:51], v[64:65] op_sel_hi:[1,0]
	v_pk_mul_f32 v[40:41], v[40:41], v[64:65] op_sel_hi:[1,0]
	v_pk_mul_f32 v[36:37], v[36:37], v[64:65] op_sel_hi:[1,0]
	v_pk_mul_f32 v[38:39], v[38:39], v[64:65] op_sel_hi:[1,0]
	v_mul_f32_e32 v57, v64, v57
	v_pk_mul_f32 v[46:47], v[82:83], v[46:47]
	v_pk_mul_f32 v[44:45], v[80:81], v[44:45]
	v_mul_f32_e32 v55, v72, v55
	v_mul_f32_e32 v98, v73, v98
	v_pk_mul_f32 v[42:43], v[42:43], v[64:65] op_sel_hi:[1,0]
	v_pk_mul_f32 v[50:51], v[90:91], v[50:51]
	v_pk_mul_f32 v[48:49], v[88:89], v[48:49]
	v_pk_mul_f32 v[40:41], v[84:85], v[40:41]
	v_pk_mul_f32 v[60:61], v[78:79], v[38:39]
	v_pk_mul_f32 v[66:67], v[76:77], v[36:37]
	v_mul_f32_e32 v57, v74, v57
	v_cvt_pk_bf16_f32 v36, v48, v49
	v_cvt_pk_bf16_f32 v37, v50, v51
	v_cvt_pk_bf16_f32 v38, v44, v45
	v_cvt_pk_bf16_f32 v39, v46, v47
	v_mov_b32_e32 v250, v55
	v_mov_b32_e32 v219, v55
	s_nop 1
	v_permlane16_swap_b32_e32 v250, v219
	v_cndmask_b32_e64 v44, v219, v250, s[100:101]
	v_mov_b32_e32 v250, v98
	v_mov_b32_e32 v219, v98
	s_nop 1
	v_permlane16_swap_b32_e32 v250, v219
	v_cndmask_b32_e64 v46, v219, v250, s[100:101]
	v_pk_mul_f32 v[42:43], v[86:87], v[42:43]
	v_mov_b32_e32 v250, v57
	v_mov_b32_e32 v219, v57
	s_nop 1
	v_permlane16_swap_b32_e32 v250, v219
	v_cndmask_b32_e64 v48, v219, v250, s[100:101]
	global_store_dwordx4 v[52:53], v[36:39], off
	v_mul_f32_e32 v45, v93, v55
	v_mul_f32_e32 v47, v65, v98
	v_cvt_pk_bf16_f32 v36, v40, v41
	v_cvt_pk_bf16_f32 v37, v42, v43
	v_cvt_pk_bf16_f32 v38, v66, v67
	v_cvt_pk_bf16_f32 v39, v60, v61
	v_mul_f32_e32 v40, 0x3d0186e2, v54
	global_store_dwordx4 v[52:53], v[36:39], off offset:64
	v_mul_f32_e32 v40, 0.15915494, v40
	v_cos_f32_e32 v41, v40
	v_mul_f32_e32 v39, v64, v56
	v_mul_f32_e32 v39, v75, v39
	v_sin_f32_e32 v40, v40
	v_mov_b32_e32 v250, v39
	v_mov_b32_e32 v219, v39
	s_nop 1
	v_permlane16_swap_b32_e32 v250, v219
	v_cndmask_b32_e64 v42, v219, v250, s[100:101]
	s_waitcnt lgkmcnt(3)
	v_cndmask_b32_e64 v36, v44, -v44, s[6:7]
	s_waitcnt lgkmcnt(2)
	v_cndmask_b32_e64 v37, v46, -v46, s[6:7]
	v_fmac_f32_e32 v45, v94, v36
	v_fmac_f32_e32 v47, v95, v37
	v_cndmask_b32_e64 v36, 0, v92, s[14:15]
	v_mul_f32_e32 v37, v97, v57
	s_waitcnt lgkmcnt(1)
	v_cndmask_b32_e64 v38, v48, -v48, s[6:7]
	v_fmac_f32_e32 v37, v36, v38
	v_cndmask_b32_e64 v36, 1.0, v41, s[14:15]
	v_mul_f32_e32 v41, 0x3c23d70a, v54
	v_cndmask_b32_e64 v38, 0, v40, s[14:15]
	v_mul_f32_e32 v40, v64, v63
	v_mul_f32_e32 v41, 0.15915494, v41
	v_mul_f32_e32 v39, v36, v39
	s_waitcnt lgkmcnt(0)
; __device__ __forceinline__ u32x4 pack8(f32x4 v0, f32x4 v1) { u32x4 w; w.x = cvt_pk_bf16(v0[0], v0[1]); w.y = cvt_pk_bf16(v0[2], v0[3]); w.z = cvt_pk_bf16(v1[0], v1[1]); w.w = cvt_pk_bf16(v1[2], v1[3]); return w; }
;     __device__ __forceinline__ void operator()(const f32x4 (&acc)[2][2][4][2], const Unit& u, int wr, int wc, int fr, int fq) const {
;     ...
;                     const u32x4 praw = *(const u32x4*)(KPE + (size_t)row * 32 + 8 * fq); float pe[8];
; #pragma unroll
;                     for (int e = 0; e < 4; ++e) { pe[2 * e] = __uint_as_float(praw[e] << 16); pe[2 * e + 1] = __uint_as_float(praw[e] & 0xffff0000u); }
;                     float ss = 0.f;
; #pragma unroll
;                     for (int bj = 0; bj < 2; ++bj)
; #pragma unroll
;                         for (int n = 0; n < 2; ++n) { const f32x4 v = acc[ai][bj][m][n]; ss += (v[0] * v[0] + v[1] * v[1]) + (v[2] * v[2] + v[3] * v[3]); }
; #pragma unroll
;                     for (int e = 0; e < 8; ++e) ss += pe[e] * pe[e];
;                     ss += __shfl_xor(ss, 16); ss += __shfl_xor(ss, 32);
;                     const float rstd = rsqrtf(ss * (1.0f / 96.0f) + EPS);
;     ...
;                     const int l = sp - CTXL; const float pos = (fq >> 1) ? (float)(l & 63) : (float)(l >> 6);
;                     f32x4 o0, o1;
; #pragma unroll
;                     for (int e = 0; e < 8; ++e) { const float own = pe[e] * rstd * (e < 4 ? gp0[e & 3] : gp1[e & 3]); const float other = __shfl_xor(own, 16);
;                         float cs = 1.f, sn = 0.f; if (lat) { const float ang = pos * invf[e]; cs = __cosf(ang); sn = __sinf(ang); }
;                         const float r = own * cs + sgn * other * sn; if (e < 4) o0[e & 3] = r; else o1[e & 3] = r; }
;                     *(u32x4*)(kd + 64 + 8 * fq) = pack8(o0, o1);
;                     if (fq < 2) *(u32x4*)(kd + 96 + 8 * fq) = (u32x4){fq == 0 ? 0x3F80u : 0u, 0u, 0u, 0u};
	v_cndmask_b32_e64 v36, v42, -v42, s[6:7]
	v_mul_f32_e32 v40, v68, v40
	v_cos_f32_e32 v42, v41
	v_sin_f32_e32 v41, v41
	v_mov_b32_e32 v250, v40
	v_mov_b32_e32 v219, v40
	s_nop 1
	v_permlane16_swap_b32_e32 v250, v219
	v_cndmask_b32_e64 v43, v219, v250, s[100:101]
	v_fmac_f32_e32 v39, v38, v36
	v_cndmask_b32_e64 v36, 1.0, v42, s[14:15]
	v_mul_f32_e32 v42, 0x3b4f3e37, v54
	v_cndmask_b32_e64 v38, 0, v41, s[14:15]
	v_mul_f32_e32 v41, v64, v62
	v_mul_f32_e32 v42, 0.15915494, v42
	v_mul_f32_e32 v40, v36, v40
	s_waitcnt lgkmcnt(0)
	v_cndmask_b32_e64 v36, v43, -v43, s[6:7]
	v_mul_f32_e32 v41, v69, v41
	v_cos_f32_e32 v43, v42
	v_sin_f32_e32 v42, v42
	v_mov_b32_e32 v250, v41
	v_mov_b32_e32 v219, v41
	s_nop 1
	v_permlane16_swap_b32_e32 v250, v219
	v_cndmask_b32_e64 v44, v219, v250, s[100:101]
	v_fmac_f32_e32 v40, v38, v36
	v_cndmask_b32_e64 v36, 1.0, v43, s[14:15]
	v_mul_f32_e32 v43, 0x3a83126f, v54
	v_cndmask_b32_e64 v38, 0, v42, s[14:15]
	v_mul_f32_e32 v42, v64, v59
	v_mul_f32_e32 v43, 0.15915494, v43
	v_mul_f32_e32 v41, v36, v41
	s_waitcnt lgkmcnt(0)
	v_cndmask_b32_e64 v36, v44, -v44, s[6:7]
	v_mul_f32_e32 v42, v70, v42
	v_cos_f32_e32 v44, v43
	v_sin_f32_e32 v43, v43
	v_mov_b32_e32 v250, v42
	v_mov_b32_e32 v219, v42
	s_nop 1
	v_permlane16_swap_b32_e32 v250, v219
	v_cndmask_b32_e64 v46, v219, v250, s[100:101]
	v_fmac_f32_e32 v41, v38, v36
	v_cndmask_b32_e64 v36, 1.0, v44, s[14:15]
	v_cndmask_b32_e64 v38, 0, v43, s[14:15]
	v_mul_f32_e32 v43, v64, v58
	v_mul_f32_e32 v44, 0x39a5cb5f, v54
	v_mul_f32_e32 v43, v71, v43
	v_mul_f32_e32 v44, 0.15915494, v44
	v_mul_f32_e32 v42, v36, v42
	s_waitcnt lgkmcnt(0)
	v_cndmask_b32_e64 v36, v46, -v46, s[6:7]
	v_cos_f32_e32 v46, v44
	v_mov_b32_e32 v250, v43
	v_mov_b32_e32 v219, v43
	s_nop 1
	v_permlane16_swap_b32_e32 v250, v219
	v_cndmask_b32_e64 v48, v219, v250, s[100:101]
	v_sin_f32_e32 v44, v44
	v_fmac_f32_e32 v42, v38, v36
	v_cndmask_b32_e64 v36, 1.0, v46, s[14:15]
	v_mul_f32_e32 v43, v36, v43
	v_cndmask_b32_e64 v38, 0, v44, s[14:15]
	s_waitcnt lgkmcnt(0)
	v_cndmask_b32_e64 v36, v48, -v48, s[6:7]
	v_fmac_f32_e32 v43, v38, v36
	v_cvt_pk_bf16_f32 v36, v45, v47
	v_cvt_pk_bf16_f32 v37, v37, v39
	v_cvt_pk_bf16_f32 v38, v40, v41
	v_mov_b32_e32 v40, v194
	v_cvt_pk_bf16_f32 v39, v42, v43
	global_store_dwordx4 v[52:53], v[36:39], off offset:128
	s_and_saveexec_b64 s[34:35], s[8:9]
	s_cbranch_execz .LBB0_1520
	v_mov_b32_e32 v40, v96
	global_store_dwordx4 v[52:53], v[0:3], off offset:192
.LBB0_1520:
	s_or_b64 exec, exec, s[34:35]
	v_lshlrev_b64 v[36:37], 6, v[182:183]
	v_lshl_add_u64 v[36:37], v[168:169], 0, v[36:37]
	v_add_co_u32_e32 v38, vcc, 0x2000, v36
	v_mul_f32_e32 v41, v33, v33
	s_nop 0
	v_addc_co_u32_e32 v39, vcc, 0, v37, vcc
	v_mov_b32_e32 v42, v240
	v_mov_b32_e32 v43, v241
	v_mov_b32_e32 v44, v242
	v_mov_b32_e32 v45, v243
	v_mul_f32_e32 v46, v35, v35
	v_mul_f32_e32 v47, v29, v29
	v_mul_f32_e32 v48, v31, v31
	v_mul_f32_e32 v49, v25, v25
	v_mul_f32_e32 v50, v27, v27
	v_fmac_f32_e32 v41, v32, v32
	v_fmac_f32_e32 v46, v34, v34
	v_fmac_f32_e32 v47, v28, v28
	v_fmac_f32_e32 v48, v30, v30
	v_mul_f32_e32 v51, v21, v21
	v_mul_f32_e32 v52, v23, v23
	v_fmac_f32_e32 v49, v24, v24
	v_fmac_f32_e32 v50, v26, v26
	v_add_f32_e32 v41, v41, v46
	v_add_f32_e32 v46, v47, v48
	v_fmac_f32_e32 v51, v20, v20
	v_fmac_f32_e32 v52, v22, v22
	v_add_f32_e32 v47, v49, v50
	v_add_f32_e32 v41, v46, v41
	v_add_f32_e32 v48, v51, v52
	v_add_f32_e32 v41, v47, v41
	v_add_f32_e32 v41, v48, v41
	v_mul_f32_e32 v53, 0.15915494, v40
	v_cos_f32_e32 v58, v53
	v_sin_f32_e32 v59, v53
	v_mul_f32_e32 v54, 0x3ea1e89b, v40
	v_mul_f32_e32 v55, 0x3dcccccd, v40
	v_mul_f32_e32 v60, 0.15915494, v54
	v_mul_f32_e32 v61, 0.15915494, v55
	v_or_b32_e32 v38, 32, v164
	v_mov_b32_e32 v39, v165
	v_lshl_add_u64 v[38:39], s[4:5], 0, v[38:39]
	v_lshlrev_b64 v[38:39], 8, v[38:39]
	v_lshl_add_u64 v[38:39], v[172:173], 0, v[38:39]
	s_waitcnt vmcnt(0)
	v_and_b32_e32 v46, 0xffff0000, v42
	v_lshlrev_b32_e32 v47, 16, v42
	v_pk_mul_f32 v[50:51], v[46:47], v[46:47]
	v_and_b32_e32 v42, 0xffff0000, v43
	v_lshlrev_b32_e32 v43, 16, v43
	v_add_f32_e32 v41, v41, v51
	v_pk_mul_f32 v[52:53], v[42:43], v[42:43]
	v_add_f32_e32 v41, v50, v41
	v_and_b32_e32 v48, 0xffff0000, v44
	v_lshlrev_b32_e32 v49, 16, v44
	v_add_f32_e32 v41, v53, v41
	v_pk_mul_f32 v[54:55], v[48:49], v[48:49]
	v_add_f32_e32 v41, v52, v41
	v_and_b32_e32 v44, 0xffff0000, v45
	v_lshlrev_b32_e32 v45, 16, v45
	v_add_f32_e32 v41, v55, v41
	v_pk_mul_f32 v[56:57], v[44:45], v[44:45]
	v_add_f32_e32 v41, v54, v41
	v_add_f32_e32 v41, v57, v41
	v_add_f32_e32 v41, v56, v41
	v_mov_b32_e32 v250, v41
	v_mov_b32_e32 v219, v41
	s_nop 1
	v_permlane16_swap_b32_e32 v250, v219
	v_cndmask_b32_e64 v50, v219, v250, s[100:101]
	v_cos_f32_e32 v51, v60
	v_sin_f32_e32 v52, v60
	v_cos_f32_e32 v53, v61
	v_cndmask_b32_e64 v56, 0, v59, s[14:15]
	s_waitcnt lgkmcnt(0)
	v_add_f32_e32 v41, v41, v50
	ds_bpermute_b32 v50, v203, v41
	v_cndmask_b32_e64 v51, 1.0, v51, s[14:15]
	v_cndmask_b32_e64 v55, 1.0, v58, s[14:15]
	v_cndmask_b32_e64 v57, 0, v52, s[14:15]
	v_cndmask_b32_e64 v58, 1.0, v53, s[14:15]
	s_waitcnt lgkmcnt(0)
; __device__ __forceinline__ u32x4 pack8(f32x4 v0, f32x4 v1) { u32x4 w; w.x = cvt_pk_bf16(v0[0], v0[1]); w.y = cvt_pk_bf16(v0[2], v0[3]); w.z = cvt_pk_bf16(v1[0], v1[1]); w.w = cvt_pk_bf16(v1[2], v1[3]); return w; }
;     __device__ __forceinline__ void operator()(const f32x4 (&acc)[2][2][4][2], const Unit& u, int wr, int wc, int fr, int fq) const {
;     ...
;                     ss += __shfl_xor(ss, 16); ss += __shfl_xor(ss, 32);
;                     const float rstd = rsqrtf(ss * (1.0f / 96.0f) + EPS);
;                     bf16_t* kd = KH + ((size_t)(b * NHEAD + h) * SPB + sp) * 128;
; #pragma unroll
;                     for (int bj = 0; bj < 2; ++bj) *(u32x4*)(kd + 32 * bj + 8 * fq) = pack8(acc[ai][bj][m][0] * rstd * g0[bj], acc[ai][bj][m][1] * rstd * g1[bj]);
;                     const int l = sp - CTXL; const float pos = (fq >> 1) ? (float)(l & 63) : (float)(l >> 6);
;                     f32x4 o0, o1;
; #pragma unroll
;                     for (int e = 0; e < 8; ++e) { const float own = pe[e] * rstd * (e < 4 ? gp0[e & 3] : gp1[e & 3]); const float other = __shfl_xor(own, 16);
;                         float cs = 1.f, sn = 0.f; if (lat) { const float ang = pos * invf[e]; cs = __cosf(ang); sn = __sinf(ang); }
;                         const float r = own * cs + sgn * other * sn; if (e < 4) o0[e & 3] = r; else o1[e & 3] = r; }
;                     *(u32x4*)(kd + 64 + 8 * fq) = pack8(o0, o1);
;                     if (fq < 2) *(u32x4*)(kd + 96 + 8 * fq) = (u32x4){fq == 0 ? 0x3F80u : 0u, 0u, 0u, 0u};
	v_add_f32_e32 v41, v41, v50
	v_fmamk_f32 v41, v41, 0x3c2aaaab, v199
	v_mul_f32_e32 v50, 0x4b800000, v41
	v_cmp_gt_f32_e32 vcc, s69, v41
	v_sin_f32_e32 v54, v61
	s_nop 0
	v_cndmask_b32_e32 v41, v41, v50, vcc
	v_rsq_f32_e32 v41, v41
	s_nop 0
	v_mul_f32_e32 v50, 0x45800000, v41
	v_cndmask_b32_e32 v50, v41, v50, vcc
	v_pk_mul_f32 v[28:29], v[28:29], v[50:51] op_sel_hi:[1,0]
	v_pk_mul_f32 v[30:31], v[30:31], v[50:51] op_sel_hi:[1,0]
	v_mul_f32_e32 v41, v50, v47
	v_mul_f32_e32 v59, v50, v46
	v_pk_mul_f32 v[32:33], v[32:33], v[50:51] op_sel_hi:[1,0]
	v_pk_mul_f32 v[34:35], v[34:35], v[50:51] op_sel_hi:[1,0]
	v_pk_mul_f32 v[24:25], v[24:25], v[50:51] op_sel_hi:[1,0]
	v_pk_mul_f32 v[20:21], v[20:21], v[50:51] op_sel_hi:[1,0]
	v_pk_mul_f32 v[22:23], v[22:23], v[50:51] op_sel_hi:[1,0]
	v_mul_f32_e32 v43, v50, v43
	v_pk_mul_f32 v[30:31], v[82:83], v[30:31]
	v_pk_mul_f32 v[28:29], v[80:81], v[28:29]
	v_mul_f32_e32 v41, v72, v41
	v_mul_f32_e32 v59, v73, v59
	v_pk_mul_f32 v[26:27], v[26:27], v[50:51] op_sel_hi:[1,0]
	v_pk_mul_f32 v[34:35], v[90:91], v[34:35]
	v_pk_mul_f32 v[32:33], v[88:89], v[32:33]
	v_pk_mul_f32 v[24:25], v[84:85], v[24:25]
	v_pk_mul_f32 v[46:47], v[78:79], v[22:23]
	v_pk_mul_f32 v[52:53], v[76:77], v[20:21]
	v_mul_f32_e32 v43, v74, v43
	v_cvt_pk_bf16_f32 v20, v32, v33
	v_cvt_pk_bf16_f32 v21, v34, v35
	v_cvt_pk_bf16_f32 v22, v28, v29
	v_cvt_pk_bf16_f32 v23, v30, v31
	v_mov_b32_e32 v250, v41
	v_mov_b32_e32 v219, v41
	s_nop 1
	v_permlane16_swap_b32_e32 v250, v219
	v_cndmask_b32_e64 v28, v219, v250, s[100:101]
	v_mov_b32_e32 v250, v59
	v_mov_b32_e32 v219, v59
	s_nop 1
	v_permlane16_swap_b32_e32 v250, v219
	v_cndmask_b32_e64 v30, v219, v250, s[100:101]
	v_pk_mul_f32 v[26:27], v[86:87], v[26:27]
	v_mov_b32_e32 v250, v43
	v_mov_b32_e32 v219, v43
	s_nop 1
	v_permlane16_swap_b32_e32 v250, v219
	v_cndmask_b32_e64 v32, v219, v250, s[100:101]
	global_store_dwordx4 v[38:39], v[20:23], off
	v_mul_f32_e32 v29, v55, v41
	v_mul_f32_e32 v31, v51, v59
	v_cvt_pk_bf16_f32 v20, v24, v25
	v_cvt_pk_bf16_f32 v21, v26, v27
	v_cvt_pk_bf16_f32 v22, v52, v53
	v_cvt_pk_bf16_f32 v23, v46, v47
	v_mul_f32_e32 v24, 0x3d0186e2, v40
	global_store_dwordx4 v[38:39], v[20:23], off offset:64
	v_mul_f32_e32 v24, 0.15915494, v24
	v_cos_f32_e32 v25, v24
	v_mul_f32_e32 v23, v50, v42
	v_mul_f32_e32 v23, v75, v23
	v_sin_f32_e32 v24, v24
	v_mov_b32_e32 v250, v23
	v_mov_b32_e32 v219, v23
	s_nop 1
	v_permlane16_swap_b32_e32 v250, v219
	v_cndmask_b32_e64 v26, v219, v250, s[100:101]
	s_waitcnt lgkmcnt(3)
	v_cndmask_b32_e64 v20, v28, -v28, s[6:7]
	s_waitcnt lgkmcnt(2)
	v_cndmask_b32_e64 v21, v30, -v30, s[6:7]
	v_fmac_f32_e32 v29, v56, v20
	v_fmac_f32_e32 v31, v57, v21
	v_cndmask_b32_e64 v20, 0, v54, s[14:15]
	v_mul_f32_e32 v21, v58, v43
	s_waitcnt lgkmcnt(1)
	v_cndmask_b32_e64 v22, v32, -v32, s[6:7]
	v_fmac_f32_e32 v21, v20, v22
	v_cndmask_b32_e64 v20, 1.0, v25, s[14:15]
	v_mul_f32_e32 v25, 0x3c23d70a, v40
	v_cndmask_b32_e64 v22, 0, v24, s[14:15]
	v_mul_f32_e32 v24, v50, v49
	v_mul_f32_e32 v25, 0.15915494, v25
	v_mul_f32_e32 v23, v20, v23
	s_waitcnt lgkmcnt(0)
	v_cndmask_b32_e64 v20, v26, -v26, s[6:7]
	v_mul_f32_e32 v24, v68, v24
	v_cos_f32_e32 v26, v25
	v_sin_f32_e32 v25, v25
	v_mov_b32_e32 v250, v24
	v_mov_b32_e32 v219, v24
	s_nop 1
	v_permlane16_swap_b32_e32 v250, v219
	v_cndmask_b32_e64 v27, v219, v250, s[100:101]
	v_fmac_f32_e32 v23, v22, v20
	v_cndmask_b32_e64 v20, 1.0, v26, s[14:15]
	v_mul_f32_e32 v26, 0x3b4f3e37, v40
	v_cndmask_b32_e64 v22, 0, v25, s[14:15]
	v_mul_f32_e32 v25, v50, v48
	v_mul_f32_e32 v26, 0.15915494, v26
	v_mul_f32_e32 v24, v20, v24
	s_waitcnt lgkmcnt(0)
	v_cndmask_b32_e64 v20, v27, -v27, s[6:7]
	v_mul_f32_e32 v25, v69, v25
	v_cos_f32_e32 v27, v26
	v_sin_f32_e32 v26, v26
	v_mov_b32_e32 v250, v25
	v_mov_b32_e32 v219, v25
	s_nop 1
	v_permlane16_swap_b32_e32 v250, v219
	v_cndmask_b32_e64 v28, v219, v250, s[100:101]
	v_fmac_f32_e32 v24, v22, v20
	v_cndmask_b32_e64 v20, 1.0, v27, s[14:15]
	v_mul_f32_e32 v27, 0x3a83126f, v40
	v_cndmask_b32_e64 v22, 0, v26, s[14:15]
	v_mul_f32_e32 v26, v50, v45
	v_mul_f32_e32 v27, 0.15915494, v27
	v_mul_f32_e32 v25, v20, v25
	s_waitcnt lgkmcnt(0)
	v_cndmask_b32_e64 v20, v28, -v28, s[6:7]
	v_mul_f32_e32 v26, v70, v26
	v_cos_f32_e32 v28, v27
	v_sin_f32_e32 v27, v27
	v_mov_b32_e32 v250, v26
	v_mov_b32_e32 v219, v26
	s_nop 1
	v_permlane16_swap_b32_e32 v250, v219
	v_cndmask_b32_e64 v30, v219, v250, s[100:101]
	v_fmac_f32_e32 v25, v22, v20
	v_cndmask_b32_e64 v20, 1.0, v28, s[14:15]
	v_cndmask_b32_e64 v22, 0, v27, s[14:15]
	v_mul_f32_e32 v27, v50, v44
	v_mul_f32_e32 v28, 0x39a5cb5f, v40
	v_mul_f32_e32 v27, v71, v27
	v_mul_f32_e32 v28, 0.15915494, v28
	v_mul_f32_e32 v26, v20, v26
	s_waitcnt lgkmcnt(0)
	v_cndmask_b32_e64 v20, v30, -v30, s[6:7]
	v_cos_f32_e32 v30, v28
	v_mov_b32_e32 v250, v27
	v_mov_b32_e32 v219, v27
	s_nop 1
	v_permlane16_swap_b32_e32 v250, v219
	v_cndmask_b32_e64 v32, v219, v250, s[100:101]
	v_sin_f32_e32 v28, v28
	v_fmac_f32_e32 v26, v22, v20
	v_cndmask_b32_e64 v20, 1.0, v30, s[14:15]
	v_mul_f32_e32 v27, v20, v27
	v_cndmask_b32_e64 v22, 0, v28, s[14:15]
	s_waitcnt lgkmcnt(0)
	v_cndmask_b32_e64 v20, v32, -v32, s[6:7]
	v_fmac_f32_e32 v27, v22, v20
	v_cvt_pk_bf16_f32 v20, v29, v31
	v_cvt_pk_bf16_f32 v21, v21, v23
	v_cvt_pk_bf16_f32 v22, v24, v25
	v_cvt_pk_bf16_f32 v23, v26, v27
	global_store_dwordx4 v[38:39], v[20:23], off offset:128
	s_nop 1
	v_mov_b32_e32 v22, v195
	s_and_saveexec_b64 s[34:35], s[8:9]
	s_cbranch_execz .LBB0_1522
	v_mov_b32_e32 v22, v96
	global_store_dwordx4 v[38:39], v[0:3], off offset:192
; __device__ __forceinline__ u32x4 pack8(f32x4 v0, f32x4 v1) { u32x4 w; w.x = cvt_pk_bf16(v0[0], v0[1]); w.y = cvt_pk_bf16(v0[2], v0[3]); w.z = cvt_pk_bf16(v1[0], v1[1]); w.w = cvt_pk_bf16(v1[2], v1[3]); return w; }
;     __device__ __forceinline__ void operator()(const f32x4 (&acc)[2][2][4][2], const Unit& u, int wr, int wc, int fr, int fq) const {
;     ...
;                     const u32x4 praw = *(const u32x4*)(KPE + (size_t)row * 32 + 8 * fq); float pe[8];
; #pragma unroll
;                     for (int e = 0; e < 4; ++e) { pe[2 * e] = __uint_as_float(praw[e] << 16); pe[2 * e + 1] = __uint_as_float(praw[e] & 0xffff0000u); }
;                     float ss = 0.f;
; #pragma unroll
;                     for (int bj = 0; bj < 2; ++bj)
; #pragma unroll
;                         for (int n = 0; n < 2; ++n) { const f32x4 v = acc[ai][bj][m][n]; ss += (v[0] * v[0] + v[1] * v[1]) + (v[2] * v[2] + v[3] * v[3]); }
; #pragma unroll
;                     for (int e = 0; e < 8; ++e) ss += pe[e] * pe[e];
;                     ss += __shfl_xor(ss, 16); ss += __shfl_xor(ss, 32);
;                     const float rstd = rsqrtf(ss * (1.0f / 96.0f) + EPS);
;                     bf16_t* kd = KH + ((size_t)(b * NHEAD + h) * SPB + sp) * 128;
; #pragma unroll
;                     for (int bj = 0; bj < 2; ++bj) *(u32x4*)(kd + 32 * bj + 8 * fq) = pack8(acc[ai][bj][m][0] * rstd * g0[bj], acc[ai][bj][m][1] * rstd * g1[bj]);
.LBB0_1522:
	s_or_b64 exec, exec, s[34:35]
	v_add_co_u32_e32 v20, vcc, 0x2000, v36
	v_mul_f32_e32 v23, v17, v17
	s_nop 0
	v_addc_co_u32_e32 v21, vcc, 0, v37, vcc
	v_mov_b32_e32 v24, v244
	v_mov_b32_e32 v25, v245
	v_mov_b32_e32 v26, v246
	v_mov_b32_e32 v27, v247
	v_mul_f32_e32 v28, v19, v19
	v_mul_f32_e32 v29, v13, v13
	v_mul_f32_e32 v30, v15, v15
	v_mul_f32_e32 v31, v9, v9
	v_mul_f32_e32 v32, v11, v11
	v_fmac_f32_e32 v23, v16, v16
	v_fmac_f32_e32 v28, v18, v18
	v_fmac_f32_e32 v29, v12, v12
	v_fmac_f32_e32 v30, v14, v14
	v_mul_f32_e32 v33, v5, v5
	v_mul_f32_e32 v34, v7, v7
	v_fmac_f32_e32 v31, v8, v8
	v_fmac_f32_e32 v32, v10, v10
	v_add_f32_e32 v23, v23, v28
	v_add_f32_e32 v28, v29, v30
	v_fmac_f32_e32 v33, v4, v4
	v_fmac_f32_e32 v34, v6, v6
	v_add_f32_e32 v29, v31, v32
	v_add_f32_e32 v23, v28, v23
	v_add_f32_e32 v30, v33, v34
	v_add_f32_e32 v23, v29, v23
	v_add_f32_e32 v23, v30, v23
	v_mul_f32_e32 v35, 0.15915494, v22
	v_cos_f32_e32 v40, v35
	v_sin_f32_e32 v41, v35
	v_mul_f32_e32 v36, 0x3ea1e89b, v22
	v_mul_f32_e32 v37, 0x3dcccccd, v22
	v_mul_f32_e32 v42, 0.15915494, v36
	v_mul_f32_e32 v43, 0.15915494, v37
	v_or_b32_e32 v164, 48, v164
	v_lshl_add_u64 v[20:21], s[4:5], 0, v[164:165]
	v_lshlrev_b64 v[20:21], 8, v[20:21]
	v_lshl_add_u64 v[20:21], v[172:173], 0, v[20:21]
	s_waitcnt vmcnt(0)
	v_and_b32_e32 v28, 0xffff0000, v24
	v_lshlrev_b32_e32 v29, 16, v24
	v_pk_mul_f32 v[32:33], v[28:29], v[28:29]
	v_and_b32_e32 v24, 0xffff0000, v25
	v_lshlrev_b32_e32 v25, 16, v25
	v_add_f32_e32 v23, v23, v33
	v_pk_mul_f32 v[34:35], v[24:25], v[24:25]
	v_add_f32_e32 v23, v32, v23
	v_and_b32_e32 v30, 0xffff0000, v26
	v_lshlrev_b32_e32 v31, 16, v26
	v_add_f32_e32 v23, v35, v23
	v_pk_mul_f32 v[36:37], v[30:31], v[30:31]
	v_add_f32_e32 v23, v34, v23
	v_and_b32_e32 v26, 0xffff0000, v27
	v_lshlrev_b32_e32 v27, 16, v27
	v_add_f32_e32 v23, v37, v23
	v_pk_mul_f32 v[38:39], v[26:27], v[26:27]
	v_add_f32_e32 v23, v36, v23
	v_add_f32_e32 v23, v39, v23
	v_add_f32_e32 v23, v38, v23
	v_mov_b32_e32 v250, v23
	v_mov_b32_e32 v219, v23
	s_nop 1
	v_permlane16_swap_b32_e32 v250, v219
	v_cndmask_b32_e64 v32, v219, v250, s[100:101]
	v_cos_f32_e32 v33, v42
	v_sin_f32_e32 v34, v42
	v_cos_f32_e32 v35, v43
	v_cndmask_b32_e64 v38, 0, v41, s[14:15]
	s_waitcnt lgkmcnt(0)
	v_add_f32_e32 v23, v23, v32
	ds_bpermute_b32 v32, v203, v23
	v_cndmask_b32_e64 v33, 1.0, v33, s[14:15]
	v_cndmask_b32_e64 v37, 1.0, v40, s[14:15]
	v_cndmask_b32_e64 v39, 0, v34, s[14:15]
	v_cndmask_b32_e64 v40, 1.0, v35, s[14:15]
	s_waitcnt lgkmcnt(0)
	v_add_f32_e32 v23, v23, v32
	v_fmamk_f32 v23, v23, 0x3c2aaaab, v199
	v_mul_f32_e32 v32, 0x4b800000, v23
	v_cmp_gt_f32_e32 vcc, s69, v23
	v_sin_f32_e32 v36, v43
	s_nop 0
	v_cndmask_b32_e32 v23, v23, v32, vcc
	v_rsq_f32_e32 v23, v23
	v_cndmask_b32_e64 v36, 0, v36, s[14:15]
	v_mul_f32_e32 v32, 0x45800000, v23
	v_cndmask_b32_e32 v32, v23, v32, vcc
	v_pk_mul_f32 v[16:17], v[16:17], v[32:33] op_sel_hi:[1,0]
	v_pk_mul_f32 v[18:19], v[18:19], v[32:33] op_sel_hi:[1,0]
	v_pk_mul_f32 v[12:13], v[12:13], v[32:33] op_sel_hi:[1,0]
	v_pk_mul_f32 v[14:15], v[14:15], v[32:33] op_sel_hi:[1,0]
	v_pk_mul_f32 v[4:5], v[4:5], v[32:33] op_sel_hi:[1,0]
	v_pk_mul_f32 v[6:7], v[6:7], v[32:33] op_sel_hi:[1,0]
	v_mul_f32_e32 v23, v32, v29
	v_mul_f32_e32 v41, v32, v28
	v_pk_mul_f32 v[8:9], v[8:9], v[32:33] op_sel_hi:[1,0]
	v_pk_mul_f32 v[10:11], v[10:11], v[32:33] op_sel_hi:[1,0]
	v_mul_f32_e32 v25, v32, v25
	v_pk_mul_f32 v[18:19], v[90:91], v[18:19]
	v_pk_mul_f32 v[16:17], v[88:89], v[16:17]
	v_pk_mul_f32 v[14:15], v[82:83], v[14:15]
	v_pk_mul_f32 v[12:13], v[80:81], v[12:13]
	v_pk_mul_f32 v[28:29], v[78:79], v[6:7]
	v_pk_mul_f32 v[34:35], v[76:77], v[4:5]
	v_mul_f32_e32 v23, v72, v23
	v_mul_f32_e32 v41, v73, v41
	v_cvt_pk_bf16_f32 v4, v16, v17
	v_cvt_pk_bf16_f32 v5, v18, v19
	v_cvt_pk_bf16_f32 v6, v12, v13
	v_cvt_pk_bf16_f32 v7, v14, v15
	v_pk_mul_f32 v[10:11], v[86:87], v[10:11]
	v_pk_mul_f32 v[8:9], v[84:85], v[8:9]
	v_mul_f32_e32 v25, v74, v25
	v_mov_b32_e32 v250, v23
	v_mov_b32_e32 v219, v23
	s_nop 1
	v_permlane16_swap_b32_e32 v250, v219
	v_cndmask_b32_e64 v12, v219, v250, s[100:101]
	v_mov_b32_e32 v250, v41
	v_mov_b32_e32 v219, v41
	s_nop 1
	v_permlane16_swap_b32_e32 v250, v219
	v_cndmask_b32_e64 v14, v219, v250, s[100:101]
	global_store_dwordx4 v[20:21], v[4:7], off
	v_mov_b32_e32 v250, v25
	v_mov_b32_e32 v219, v25
	s_nop 1
	v_permlane16_swap_b32_e32 v250, v219
	v_cndmask_b32_e64 v16, v219, v250, s[100:101]
	v_mul_f32_e32 v13, v37, v23
	v_cvt_pk_bf16_f32 v4, v8, v9
	v_cvt_pk_bf16_f32 v5, v10, v11
	v_cvt_pk_bf16_f32 v6, v34, v35
	v_cvt_pk_bf16_f32 v7, v28, v29
	global_store_dwordx4 v[20:21], v[4:7], off offset:64
	v_mul_f32_e32 v15, v33, v41
	s_nop 0
	v_mul_f32_e32 v6, v32, v24
	v_mul_f32_e32 v7, 0x3d0186e2, v22
	v_mul_f32_e32 v6, v75, v6
	v_mul_f32_e32 v7, 0.15915494, v7
	v_cos_f32_e32 v8, v7
	v_mov_b32_e32 v250, v6
	v_mov_b32_e32 v219, v6
	s_nop 1
	v_permlane16_swap_b32_e32 v250, v219
	v_cndmask_b32_e64 v9, v219, v250, s[100:101]
	s_waitcnt lgkmcnt(3)
; __device__ __forceinline__ u32x4 pack8(f32x4 v0, f32x4 v1) { u32x4 w; w.x = cvt_pk_bf16(v0[0], v0[1]); w.y = cvt_pk_bf16(v0[2], v0[3]); w.z = cvt_pk_bf16(v1[0], v1[1]); w.w = cvt_pk_bf16(v1[2], v1[3]); return w; }
;     __device__ __forceinline__ void operator()(const f32x4 (&acc)[2][2][4][2], const Unit& u, int wr, int wc, int fr, int fq) const {
;     ...
;                     const int l = sp - CTXL; const float pos = (fq >> 1) ? (float)(l & 63) : (float)(l >> 6);
;                     f32x4 o0, o1;
; #pragma unroll
;                     for (int e = 0; e < 8; ++e) { const float own = pe[e] * rstd * (e < 4 ? gp0[e & 3] : gp1[e & 3]); const float other = __shfl_xor(own, 16);
;                         float cs = 1.f, sn = 0.f; if (lat) { const float ang = pos * invf[e]; cs = __cosf(ang); sn = __sinf(ang); }
;                         const float r = own * cs + sgn * other * sn; if (e < 4) o0[e & 3] = r; else o1[e & 3] = r; }
;                     *(u32x4*)(kd + 64 + 8 * fq) = pack8(o0, o1);
;                     if (fq < 2) *(u32x4*)(kd + 96 + 8 * fq) = (u32x4){fq == 0 ? 0x3F80u : 0u, 0u, 0u, 0u};
	v_cndmask_b32_e64 v4, v12, -v12, s[6:7]
	s_waitcnt lgkmcnt(2)
	v_cndmask_b32_e64 v5, v14, -v14, s[6:7]
	v_fmac_f32_e32 v13, v38, v4
	v_fmac_f32_e32 v15, v39, v5
	v_mul_f32_e32 v5, v40, v25
	s_waitcnt lgkmcnt(1)
	v_cndmask_b32_e64 v4, v16, -v16, s[6:7]
	v_fmac_f32_e32 v5, v36, v4
	v_cndmask_b32_e64 v4, 1.0, v8, s[14:15]
	v_mul_f32_e32 v6, v4, v6
	s_waitcnt lgkmcnt(0)
	v_cndmask_b32_e64 v4, v9, -v9, s[6:7]
	v_mul_f32_e32 v9, 0x3c23d70a, v22
	v_sin_f32_e32 v7, v7
	v_mul_f32_e32 v8, v32, v31
	v_mul_f32_e32 v9, 0.15915494, v9
	v_mul_f32_e32 v8, v68, v8
	v_cos_f32_e32 v10, v9
	v_sin_f32_e32 v9, v9
	v_mov_b32_e32 v250, v8
	v_mov_b32_e32 v219, v8
	s_nop 1
	v_permlane16_swap_b32_e32 v250, v219
	v_cndmask_b32_e64 v11, v219, v250, s[100:101]
	v_cndmask_b32_e64 v7, 0, v7, s[14:15]
	v_fmac_f32_e32 v6, v7, v4
	v_cndmask_b32_e64 v4, 1.0, v10, s[14:15]
	v_mul_f32_e32 v10, 0x3b4f3e37, v22
	v_cndmask_b32_e64 v7, 0, v9, s[14:15]
	v_mul_f32_e32 v9, v32, v30
	v_mul_f32_e32 v10, 0.15915494, v10
	v_mul_f32_e32 v8, v4, v8
	s_waitcnt lgkmcnt(0)
	v_cndmask_b32_e64 v4, v11, -v11, s[6:7]
	v_mul_f32_e32 v9, v69, v9
	v_cos_f32_e32 v11, v10
	v_sin_f32_e32 v10, v10
	v_mov_b32_e32 v250, v9
	v_mov_b32_e32 v219, v9
	s_nop 1
	v_permlane16_swap_b32_e32 v250, v219
	v_cndmask_b32_e64 v12, v219, v250, s[100:101]
	v_fmac_f32_e32 v8, v7, v4
	v_cndmask_b32_e64 v4, 1.0, v11, s[14:15]
	v_mul_f32_e32 v11, 0x3a83126f, v22
	v_cndmask_b32_e64 v7, 0, v10, s[14:15]
	v_mul_f32_e32 v10, v32, v27
	v_mul_f32_e32 v11, 0.15915494, v11
	v_mul_f32_e32 v9, v4, v9
	s_waitcnt lgkmcnt(0)
	v_cndmask_b32_e64 v4, v12, -v12, s[6:7]
	v_mul_f32_e32 v10, v70, v10
	v_cos_f32_e32 v12, v11
	v_sin_f32_e32 v11, v11
	v_mov_b32_e32 v250, v10
	v_mov_b32_e32 v219, v10
	s_nop 1
	v_permlane16_swap_b32_e32 v250, v219
	v_cndmask_b32_e64 v14, v219, v250, s[100:101]
	v_fmac_f32_e32 v9, v7, v4
	v_cndmask_b32_e64 v4, 1.0, v12, s[14:15]
	v_cndmask_b32_e64 v7, 0, v11, s[14:15]
	v_mul_f32_e32 v11, v32, v26
	v_mul_f32_e32 v12, 0x39a5cb5f, v22
	v_mul_f32_e32 v11, v71, v11
	v_mul_f32_e32 v12, 0.15915494, v12
	v_mul_f32_e32 v10, v4, v10
	s_waitcnt lgkmcnt(0)
	v_cndmask_b32_e64 v4, v14, -v14, s[6:7]
	v_cos_f32_e32 v14, v12
	v_mov_b32_e32 v250, v11
	v_mov_b32_e32 v219, v11
	s_nop 1
	v_permlane16_swap_b32_e32 v250, v219
	v_cndmask_b32_e64 v16, v219, v250, s[100:101]
	v_sin_f32_e32 v12, v12
	v_fmac_f32_e32 v10, v7, v4
	v_cndmask_b32_e64 v4, 1.0, v14, s[14:15]
	v_mul_f32_e32 v11, v4, v11
	v_cndmask_b32_e64 v7, 0, v12, s[14:15]
	s_waitcnt lgkmcnt(0)
	v_cndmask_b32_e64 v4, v16, -v16, s[6:7]
	v_fmac_f32_e32 v11, v7, v4
	v_cvt_pk_bf16_f32 v4, v13, v15
	v_cvt_pk_bf16_f32 v5, v5, v6
	v_cvt_pk_bf16_f32 v6, v8, v9
	v_cvt_pk_bf16_f32 v7, v10, v11
	global_store_dwordx4 v[20:21], v[4:7], off offset:128
	s_and_saveexec_b64 s[4:5], s[8:9]
	s_cbranch_execz .LBB0_1524
	global_store_dwordx4 v[20:21], v[0:3], off offset:192
